# v81 + the five K-loop heads aligned to 8 bytes (.p2align 3): E/H/I loops were at offset 4 mod 8
# speedup vs baseline: 1.0154x; 1.0154x over previous
.LBB0_266:
	s_xor_b64 s[2:3], s[2:3], -1
	s_mov_b32 s34, s74
	s_add_i32 s74, s74, 1
	s_cmp_lt_u32 s34, 5
	s_mov_b64 s[4:5], s[10:11]
	s_mov_b32 s10, s75
	s_cselect_b64 s[14:15], -1, 0
	s_add_i32 s75, s74, s16
	s_mov_b64 s[12:13], s[8:9]
	s_and_b64 s[8:9], s[14:15], exec
	s_cselect_b32 s8, s75, s10
	s_cselect_b32 s10, s6, s6
	s_ashr_i32 s11, s10, 31
	s_lshl_b64 s[10:11], s[10:11], 19
	s_add_u32 s10, s80, s10
	s_addc_u32 s11, s81, s11
	s_and_b64 s[44:45], s[14:15], exec
	s_cselect_b32 s44, s11, s5
	s_cselect_b32 s45, s10, s4
	s_ashr_i32 s9, s8, 31
	s_lshl_b64 s[8:9], s[8:9], 19
	v_readlane_b32 s47, v255, 14
	s_add_u32 s8, s47, s8
	v_readlane_b32 s47, v255, 15
	s_addc_u32 s9, s47, s9
	s_and_b64 s[14:15], s[14:15], exec
	s_cselect_b32 s47, s9, s13
	s_cselect_b32 s55, s8, s12
	s_add_u32 s4, s4, 0x40080
	s_addc_u32 s5, s5, 0
	s_add_u32 s78, s12, 0x100
	s_addc_u32 s79, s13, 0
	s_mov_b32 s85, -2
	s_waitcnt lgkmcnt(0)
	s_add_i32 s86, 0, 0x10000
	v_add_u32_e32 v0, s86, v150
	v_add_u32_e32 v189, 0x10000, v150
	ds_read_b128 v[142:145], v0
	ds_read_b128 v[146:149], v0 offset:1024
	ds_read_b128 v[152:155], v0 offset:2048
	ds_read_b128 v[156:159], v0 offset:3072
	s_add_u32 s12, s4, 0xfffc0080
	s_addc_u32 s13, s5, -1
	s_cmp_eq_u32 s85, 12
	s_cselect_b32 s15, s44, s13
	s_cselect_b32 s14, s45, s12
	s_cselect_b32 s13, s47, s79
	s_cselect_b32 s12, s55, s78
	s_add_i32 m0, s7, 0xc000
	ds_read_b128 v[160:163], v151
	ds_read_b128 v[164:167], v151 offset:1024
	ds_read_b128 v[168:171], v151 offset:2048
	ds_read_b128 v[172:175], v151 offset:3072
	ds_read_b128 v[176:179], v151 offset:4096
	ds_read_b128 v[180:183], v151 offset:5120
	ds_read_b128 v[184:187], v151 offset:6144
	global_load_lds_dwordx4 v138, s[4:5]
	s_add_i32 m0, s7, 0xe000
	ds_read_b128 v[190:193], v151 offset:7168
	global_load_lds_dwordx4 v140, s[4:5]
	s_waitcnt lgkmcnt(8)
	s_barrier
	s_waitcnt lgkmcnt(0)
	v_mfma_f32_16x16x32_bf16 v[126:129], v[142:145], v[160:163], 0
	v_mfma_f32_16x16x32_bf16 v[122:125], v[152:155], v[160:163], 0
	v_mfma_f32_16x16x32_bf16 v[110:113], v[142:145], v[168:171], 0
	v_mfma_f32_16x16x32_bf16 v[106:109], v[152:155], v[168:171], 0
	v_mfma_f32_16x16x32_bf16 v[94:97], v[142:145], v[176:179], 0
	v_mfma_f32_16x16x32_bf16 v[90:93], v[152:155], v[176:179], 0
	v_mfma_f32_16x16x32_bf16 v[78:81], v[142:145], v[184:187], 0
	v_mfma_f32_16x16x32_bf16 v[74:77], v[152:155], v[184:187], 0
	v_mfma_f32_16x16x32_bf16 v[126:129], v[146:149], v[164:167], v[126:129]
	v_mfma_f32_16x16x32_bf16 v[122:125], v[156:159], v[164:167], v[122:125]
	v_mfma_f32_16x16x32_bf16 v[110:113], v[146:149], v[172:175], v[110:113]
	v_mfma_f32_16x16x32_bf16 v[106:109], v[156:159], v[172:175], v[106:109]
	v_mfma_f32_16x16x32_bf16 v[94:97], v[146:149], v[180:183], v[94:97]
	v_mfma_f32_16x16x32_bf16 v[90:93], v[156:159], v[180:183], v[90:93]
	v_mfma_f32_16x16x32_bf16 v[78:81], v[146:149], v[190:193], v[78:81]
	v_mfma_f32_16x16x32_bf16 v[74:77], v[156:159], v[190:193], v[74:77]
	s_barrier
	s_add_i32 m0, s22, 0x10000
	ds_read_b128 v[194:197], v189 offset:16384
	ds_read_b128 v[198:201], v189 offset:17408
	ds_read_b128 v[202:205], v189 offset:18432
	global_load_lds_dwordx4 v134, s[12:13]
	s_add_i32 m0, s22, 0x12000
	ds_read_b128 v[206:209], v189 offset:19456
	global_load_lds_dwordx4 v130, s[12:13]
	s_barrier
	s_waitcnt lgkmcnt(0)
	v_mfma_f32_16x16x32_bf16 v[118:121], v[194:197], v[160:163], 0
	v_mfma_f32_16x16x32_bf16 v[114:117], v[202:205], v[160:163], 0
	v_mfma_f32_16x16x32_bf16 v[102:105], v[194:197], v[168:171], 0
	v_mfma_f32_16x16x32_bf16 v[98:101], v[202:205], v[168:171], 0
	v_mfma_f32_16x16x32_bf16 v[86:89], v[194:197], v[176:179], 0
	v_mfma_f32_16x16x32_bf16 v[82:85], v[202:205], v[176:179], 0
	v_mfma_f32_16x16x32_bf16 v[70:73], v[194:197], v[184:187], 0
	v_mfma_f32_16x16x32_bf16 v[66:69], v[202:205], v[184:187], 0
	v_mfma_f32_16x16x32_bf16 v[118:121], v[198:201], v[164:167], v[118:121]
	v_mfma_f32_16x16x32_bf16 v[114:117], v[206:209], v[164:167], v[114:117]
	v_mfma_f32_16x16x32_bf16 v[102:105], v[198:201], v[172:175], v[102:105]
	v_mfma_f32_16x16x32_bf16 v[98:101], v[206:209], v[172:175], v[98:101]
	v_mfma_f32_16x16x32_bf16 v[86:89], v[198:201], v[180:183], v[86:89]
	v_mfma_f32_16x16x32_bf16 v[82:85], v[206:209], v[180:183], v[82:85]
	v_mfma_f32_16x16x32_bf16 v[70:73], v[198:201], v[190:193], v[70:73]
	v_mfma_f32_16x16x32_bf16 v[66:69], v[206:209], v[190:193], v[66:69]
	s_mov_b32 m0, s7
	s_mov_b64 s[100:101], s[14:15]
	s_barrier
	ds_read_b128 v[160:163], v151 offset:16384
	ds_read_b128 v[164:167], v151 offset:17408
	ds_read_b128 v[168:171], v151 offset:18432
	ds_read_b128 v[172:175], v151 offset:19456
	ds_read_b128 v[176:179], v151 offset:20480
	ds_read_b128 v[180:183], v151 offset:21504
	ds_read_b128 v[184:187], v151 offset:22528
	global_load_lds_dwordx4 v136, s[100:101]
	s_mov_b32 m0, s23
	ds_read_b128 v[190:193], v151 offset:23552
	global_load_lds_dwordx4 v132, s[100:101]
	s_waitcnt vmcnt(10)
	s_barrier
	s_waitcnt lgkmcnt(0)
	v_mfma_f32_16x16x32_bf16 v[62:65], v[142:145], v[160:163], 0
	v_mfma_f32_16x16x32_bf16 v[58:61], v[152:155], v[160:163], 0
	v_mfma_f32_16x16x32_bf16 v[46:49], v[142:145], v[168:171], 0
	v_mfma_f32_16x16x32_bf16 v[42:45], v[152:155], v[168:171], 0
	v_mfma_f32_16x16x32_bf16 v[30:33], v[142:145], v[176:179], 0
	v_mfma_f32_16x16x32_bf16 v[26:29], v[152:155], v[176:179], 0
	v_mfma_f32_16x16x32_bf16 v[14:17], v[142:145], v[184:187], 0
	v_mfma_f32_16x16x32_bf16 v[10:13], v[152:155], v[184:187], 0
	v_mfma_f32_16x16x32_bf16 v[62:65], v[146:149], v[164:167], v[62:65]
	v_mfma_f32_16x16x32_bf16 v[58:61], v[156:159], v[164:167], v[58:61]
	v_mfma_f32_16x16x32_bf16 v[46:49], v[146:149], v[172:175], v[46:49]
	v_mfma_f32_16x16x32_bf16 v[42:45], v[156:159], v[172:175], v[42:45]
	v_mfma_f32_16x16x32_bf16 v[30:33], v[146:149], v[180:183], v[30:33]
	v_mfma_f32_16x16x32_bf16 v[26:29], v[156:159], v[180:183], v[26:29]
	v_mfma_f32_16x16x32_bf16 v[14:17], v[146:149], v[190:193], v[14:17]
	v_mfma_f32_16x16x32_bf16 v[10:13], v[156:159], v[190:193], v[10:13]
	s_barrier
	s_add_u32 s86, s12, 0x40000
	s_addc_u32 s87, s13, 0
	s_add_i32 m0, s22, 0x14000
	s_nop 0
	global_load_lds_dwordx4 v134, s[86:87]
	s_add_i32 m0, s22, 0x16000
	s_nop 0
	global_load_lds_dwordx4 v130, s[86:87]
	ds_read_b128 v[142:145], v189 offset:32768
	ds_read_b128 v[146:149], v189 offset:33792
	ds_read_b128 v[152:155], v189 offset:34816
	ds_read_b128 v[156:159], v189 offset:35840
	s_waitcnt vmcnt(6)
	s_barrier
	v_mfma_f32_16x16x32_bf16 v[54:57], v[194:197], v[160:163], 0
	v_mfma_f32_16x16x32_bf16 v[50:53], v[202:205], v[160:163], 0
	v_mfma_f32_16x16x32_bf16 v[38:41], v[194:197], v[168:171], 0
	v_mfma_f32_16x16x32_bf16 v[34:37], v[202:205], v[168:171], 0
	v_mfma_f32_16x16x32_bf16 v[22:25], v[194:197], v[176:179], 0
	v_mfma_f32_16x16x32_bf16 v[18:21], v[202:205], v[176:179], 0
	v_mfma_f32_16x16x32_bf16 v[6:9], v[194:197], v[184:187], 0
	v_mfma_f32_16x16x32_bf16 v[2:5], v[202:205], v[184:187], 0
	v_mfma_f32_16x16x32_bf16 v[54:57], v[198:201], v[164:167], v[54:57]
	v_mfma_f32_16x16x32_bf16 v[50:53], v[206:209], v[164:167], v[50:53]
	v_mfma_f32_16x16x32_bf16 v[38:41], v[198:201], v[172:175], v[38:41]
	v_mfma_f32_16x16x32_bf16 v[34:37], v[206:209], v[172:175], v[34:37]
	v_mfma_f32_16x16x32_bf16 v[22:25], v[198:201], v[180:183], v[22:25]
	v_mfma_f32_16x16x32_bf16 v[18:21], v[206:209], v[180:183], v[18:21]
	v_mfma_f32_16x16x32_bf16 v[6:9], v[198:201], v[190:193], v[6:9]
	v_mfma_f32_16x16x32_bf16 v[2:5], v[206:209], v[190:193], v[2:5]
	s_barrier
	s_add_u32 s14, s14, 0x40000
	s_addc_u32 s15, s15, 0
	s_mov_b32 m0, s28
	ds_read_b128 v[160:163], v151 offset:32768
	ds_read_b128 v[164:167], v151 offset:33792
	ds_read_b128 v[168:171], v151 offset:34816
	ds_read_b128 v[172:175], v151 offset:35840
	ds_read_b128 v[176:179], v151 offset:36864
	ds_read_b128 v[180:183], v151 offset:37888
	ds_read_b128 v[184:187], v151 offset:38912
	global_load_lds_dwordx4 v136, s[14:15]
	s_mov_b32 m0, s29
	ds_read_b128 v[190:193], v151 offset:39936
	global_load_lds_dwordx4 v132, s[14:15]
	s_waitcnt lgkmcnt(8)
	s_barrier
	s_waitcnt lgkmcnt(0)
	v_mfma_f32_16x16x32_bf16 v[126:129], v[142:145], v[160:163], v[126:129]
	v_mfma_f32_16x16x32_bf16 v[122:125], v[152:155], v[160:163], v[122:125]
	v_mfma_f32_16x16x32_bf16 v[110:113], v[142:145], v[168:171], v[110:113]
	v_mfma_f32_16x16x32_bf16 v[106:109], v[152:155], v[168:171], v[106:109]
	v_mfma_f32_16x16x32_bf16 v[94:97], v[142:145], v[176:179], v[94:97]
	v_mfma_f32_16x16x32_bf16 v[90:93], v[152:155], v[176:179], v[90:93]
	v_mfma_f32_16x16x32_bf16 v[78:81], v[142:145], v[184:187], v[78:81]
	v_mfma_f32_16x16x32_bf16 v[74:77], v[152:155], v[184:187], v[74:77]
	v_mfma_f32_16x16x32_bf16 v[126:129], v[146:149], v[164:167], v[126:129]
	v_mfma_f32_16x16x32_bf16 v[122:125], v[156:159], v[164:167], v[122:125]
	v_mfma_f32_16x16x32_bf16 v[110:113], v[146:149], v[172:175], v[110:113]
	v_mfma_f32_16x16x32_bf16 v[106:109], v[156:159], v[172:175], v[106:109]
	v_mfma_f32_16x16x32_bf16 v[94:97], v[146:149], v[180:183], v[94:97]
	v_mfma_f32_16x16x32_bf16 v[90:93], v[156:159], v[180:183], v[90:93]
	v_mfma_f32_16x16x32_bf16 v[78:81], v[146:149], v[190:193], v[78:81]
	v_mfma_f32_16x16x32_bf16 v[74:77], v[156:159], v[190:193], v[74:77]
	s_barrier
	s_add_i32 m0, s22, 0x18000
	ds_read_b128 v[194:197], v189 offset:49152
	ds_read_b128 v[198:201], v189 offset:50176
	ds_read_b128 v[202:205], v189 offset:51200
	ds_read_b128 v[206:209], v189 offset:52224
	s_add_u32 s98, s12, s40
	s_addc_u32 s99, s13, s41
	global_load_lds_dwordx4 v134, s[98:99]
	s_add_i32 m0, s22, 0x1a000
	s_nop 0
	global_load_lds_dwordx4 v130, s[98:99]
	s_barrier
	s_waitcnt lgkmcnt(0)
	v_mfma_f32_16x16x32_bf16 v[118:121], v[194:197], v[160:163], v[118:121]
	v_mfma_f32_16x16x32_bf16 v[114:117], v[202:205], v[160:163], v[114:117]
	v_mfma_f32_16x16x32_bf16 v[102:105], v[194:197], v[168:171], v[102:105]
	v_mfma_f32_16x16x32_bf16 v[98:101], v[202:205], v[168:171], v[98:101]
	v_mfma_f32_16x16x32_bf16 v[86:89], v[194:197], v[176:179], v[86:89]
	v_mfma_f32_16x16x32_bf16 v[82:85], v[202:205], v[176:179], v[82:85]
	v_mfma_f32_16x16x32_bf16 v[70:73], v[194:197], v[184:187], v[70:73]
	v_mfma_f32_16x16x32_bf16 v[66:69], v[202:205], v[184:187], v[66:69]
	v_mfma_f32_16x16x32_bf16 v[118:121], v[198:201], v[164:167], v[118:121]
	v_mfma_f32_16x16x32_bf16 v[114:117], v[206:209], v[164:167], v[114:117]
	v_mfma_f32_16x16x32_bf16 v[102:105], v[198:201], v[172:175], v[102:105]
	v_mfma_f32_16x16x32_bf16 v[98:101], v[206:209], v[172:175], v[98:101]
	v_mfma_f32_16x16x32_bf16 v[86:89], v[198:201], v[180:183], v[86:89]
	v_mfma_f32_16x16x32_bf16 v[82:85], v[206:209], v[180:183], v[82:85]
	v_mfma_f32_16x16x32_bf16 v[70:73], v[198:201], v[190:193], v[70:73]
	v_mfma_f32_16x16x32_bf16 v[66:69], v[206:209], v[190:193], v[66:69]
	s_mov_b32 m0, s38
	s_barrier
	ds_read_b128 v[160:163], v151 offset:49152
	ds_read_b128 v[164:167], v151 offset:50176
	ds_read_b128 v[168:171], v151 offset:51200
	ds_read_b128 v[172:175], v151 offset:52224
	ds_read_b128 v[176:179], v151 offset:53248
	ds_read_b128 v[180:183], v151 offset:54272
	ds_read_b128 v[184:187], v151 offset:55296
	ds_read_b128 v[190:193], v151 offset:56320
	s_add_u32 s98, s100, s40
	s_addc_u32 s99, s101, s41
	global_load_lds_dwordx4 v136, s[98:99]
	s_mov_b32 m0, s39
	s_nop 0
	global_load_lds_dwordx4 v132, s[98:99]
	s_waitcnt vmcnt(10)
	s_barrier
	s_waitcnt lgkmcnt(0)
	v_mfma_f32_16x16x32_bf16 v[62:65], v[142:145], v[160:163], v[62:65]
	v_mfma_f32_16x16x32_bf16 v[58:61], v[152:155], v[160:163], v[58:61]
	v_mfma_f32_16x16x32_bf16 v[46:49], v[142:145], v[168:171], v[46:49]
	v_mfma_f32_16x16x32_bf16 v[42:45], v[152:155], v[168:171], v[42:45]
	v_mfma_f32_16x16x32_bf16 v[30:33], v[142:145], v[176:179], v[30:33]
	v_mfma_f32_16x16x32_bf16 v[26:29], v[152:155], v[176:179], v[26:29]
	v_mfma_f32_16x16x32_bf16 v[14:17], v[142:145], v[184:187], v[14:17]
	v_mfma_f32_16x16x32_bf16 v[10:13], v[152:155], v[184:187], v[10:13]
	v_mfma_f32_16x16x32_bf16 v[62:65], v[146:149], v[164:167], v[62:65]
	v_mfma_f32_16x16x32_bf16 v[58:61], v[156:159], v[164:167], v[58:61]
	v_mfma_f32_16x16x32_bf16 v[46:49], v[146:149], v[172:175], v[46:49]
	v_mfma_f32_16x16x32_bf16 v[42:45], v[156:159], v[172:175], v[42:45]
	v_mfma_f32_16x16x32_bf16 v[30:33], v[146:149], v[180:183], v[30:33]
	v_mfma_f32_16x16x32_bf16 v[26:29], v[156:159], v[180:183], v[26:29]
	v_mfma_f32_16x16x32_bf16 v[14:17], v[146:149], v[190:193], v[14:17]
	v_mfma_f32_16x16x32_bf16 v[10:13], v[156:159], v[190:193], v[10:13]
	s_barrier
	s_add_u32 s12, s12, 0x40080
	s_addc_u32 s13, s13, 0
	s_add_i32 m0, s22, 0x1c000
	s_nop 0
	global_load_lds_dwordx4 v134, s[12:13]
	s_add_i32 m0, s22, 0x1e000
	s_nop 0
	global_load_lds_dwordx4 v130, s[12:13]
	ds_read_b128 v[142:145], v189
	ds_read_b128 v[146:149], v189 offset:1024
	ds_read_b128 v[152:155], v189 offset:2048
	ds_read_b128 v[156:159], v189 offset:3072
	s_waitcnt vmcnt(6)
	s_barrier
	v_mfma_f32_16x16x32_bf16 v[54:57], v[194:197], v[160:163], v[54:57]
	v_mfma_f32_16x16x32_bf16 v[50:53], v[202:205], v[160:163], v[50:53]
	v_mfma_f32_16x16x32_bf16 v[38:41], v[194:197], v[168:171], v[38:41]
	v_mfma_f32_16x16x32_bf16 v[34:37], v[202:205], v[168:171], v[34:37]
	v_mfma_f32_16x16x32_bf16 v[22:25], v[194:197], v[176:179], v[22:25]
	v_mfma_f32_16x16x32_bf16 v[18:21], v[202:205], v[176:179], v[18:21]
	v_mfma_f32_16x16x32_bf16 v[6:9], v[194:197], v[184:187], v[6:9]
	v_mfma_f32_16x16x32_bf16 v[2:5], v[202:205], v[184:187], v[2:5]
	v_mfma_f32_16x16x32_bf16 v[54:57], v[198:201], v[164:167], v[54:57]
	v_mfma_f32_16x16x32_bf16 v[50:53], v[206:209], v[164:167], v[50:53]
	v_mfma_f32_16x16x32_bf16 v[38:41], v[198:201], v[172:175], v[38:41]
	v_mfma_f32_16x16x32_bf16 v[34:37], v[206:209], v[172:175], v[34:37]
	v_mfma_f32_16x16x32_bf16 v[22:25], v[198:201], v[180:183], v[22:25]
	v_mfma_f32_16x16x32_bf16 v[18:21], v[206:209], v[180:183], v[18:21]
	v_mfma_f32_16x16x32_bf16 v[6:9], v[198:201], v[190:193], v[6:9]
	v_mfma_f32_16x16x32_bf16 v[2:5], v[206:209], v[190:193], v[2:5]
	s_add_i32 s85, s85, 2
	s_add_u32 s4, s4, 0x100
	s_addc_u32 s5, s5, 0
	s_add_u32 s78, s78, 0x100
	s_addc_u32 s79, s79, 0
	s_add_u32 s12, s4, 0xfffc0080
	s_addc_u32 s13, s5, -1
	s_cmp_eq_u32 s85, 12
	s_cselect_b32 s15, s44, s13
	s_cselect_b32 s14, s45, s12
	s_cselect_b32 s13, s47, s79
	s_cselect_b32 s12, s55, s78
	s_cmp_gt_u32 s85, 13
	s_barrier
	.p2align 3

.LBB0_837:
	s_ashr_i32 s15, s14, 31
	s_lshl_b64 s[78:79], s[14:15], 19
	s_add_u32 s84, s36, s78
	s_addc_u32 s85, s37, s79
	s_and_b64 s[4:5], s[4:5], exec
	s_cselect_b32 s15, s85, s91
	s_cselect_b32 s23, s84, s90
	s_add_u32 s34, s90, 0x100
	s_addc_u32 s75, s91, 0
	s_mov_b32 s78, -2
	s_waitcnt lgkmcnt(0)
	s_add_i32 s79, 0, 0x10000
	v_add_u32_e32 v142, s79, v212
	v_add_u32_e32 v189, 0x10000, v212
	ds_read_b128 v[130:133], v142
	ds_read_b128 v[134:137], v142 offset:1024
	ds_read_b128 v[138:141], v142 offset:2048
	ds_read_b128 v[142:145], v142 offset:3072
	s_add_u32 s4, s88, 0x100
	s_addc_u32 s5, s89, 0
	s_cmp_eq_u32 s78, 12
	s_cselect_b32 s93, s17, s5
	s_cselect_b32 s92, s16, s4
	s_cselect_b32 s91, s15, s75
	s_cselect_b32 s90, s23, s34
	v_lshl_add_u64 v[178:179], s[88:89], 0, v[196:197]
	s_add_i32 m0, s39, 0xc000
	ds_read_b128 v[146:149], v213
	ds_read_b128 v[150:153], v213 offset:1024
	ds_read_b128 v[154:157], v213 offset:2048
	ds_read_b128 v[158:161], v213 offset:3072
	ds_read_b128 v[162:165], v213 offset:4096
	ds_read_b128 v[166:169], v213 offset:5120
	ds_read_b128 v[170:173], v213 offset:6144
	ds_read_b128 v[174:177], v213 offset:7168
	global_load_lds_dwordx4 v[178:179], off
	s_add_i32 m0, s39, 0xe000
	v_lshl_add_u64 v[178:179], s[88:89], 0, v[198:199]
	global_load_lds_dwordx4 v[178:179], off
	s_waitcnt lgkmcnt(8)
	s_barrier
	s_waitcnt lgkmcnt(0)
	v_mfma_f32_16x16x32_bf16 v[126:129], v[130:133], v[146:149], 0
	v_mfma_f32_16x16x32_bf16 v[122:125], v[138:141], v[146:149], 0
	v_mfma_f32_16x16x32_bf16 v[110:113], v[130:133], v[154:157], 0
	v_mfma_f32_16x16x32_bf16 v[106:109], v[138:141], v[154:157], 0
	v_mfma_f32_16x16x32_bf16 v[94:97], v[130:133], v[162:165], 0
	v_mfma_f32_16x16x32_bf16 v[90:93], v[138:141], v[162:165], 0
	v_mfma_f32_16x16x32_bf16 v[78:81], v[130:133], v[170:173], 0
	v_mfma_f32_16x16x32_bf16 v[74:77], v[138:141], v[170:173], 0
	v_mfma_f32_16x16x32_bf16 v[126:129], v[134:137], v[150:153], v[126:129]
	v_mfma_f32_16x16x32_bf16 v[122:125], v[142:145], v[150:153], v[122:125]
	v_mfma_f32_16x16x32_bf16 v[110:113], v[134:137], v[158:161], v[110:113]
	v_mfma_f32_16x16x32_bf16 v[106:109], v[142:145], v[158:161], v[106:109]
	v_mfma_f32_16x16x32_bf16 v[94:97], v[134:137], v[166:169], v[94:97]
	v_mfma_f32_16x16x32_bf16 v[90:93], v[142:145], v[166:169], v[90:93]
	v_mfma_f32_16x16x32_bf16 v[78:81], v[134:137], v[174:177], v[78:81]
	v_mfma_f32_16x16x32_bf16 v[74:77], v[142:145], v[174:177], v[74:77]
	s_barrier
	ds_read_b128 v[178:181], v189 offset:16384
	ds_read_b128 v[182:185], v189 offset:17408
	ds_read_b128 v[200:203], v189 offset:18432
	ds_read_b128 v[204:207], v189 offset:19456
	s_add_i32 m0, s38, 0x10000
	s_nop 0
	global_load_lds_dwordx4 v0, s[90:91]
	s_add_i32 m0, s38, 0x12000
	s_nop 0
	global_load_lds_dwordx4 v194, s[90:91]
	s_barrier
	s_waitcnt lgkmcnt(0)
	v_mfma_f32_16x16x32_bf16 v[118:121], v[178:181], v[146:149], 0
	v_mfma_f32_16x16x32_bf16 v[114:117], v[200:203], v[146:149], 0
	v_mfma_f32_16x16x32_bf16 v[102:105], v[178:181], v[154:157], 0
	v_mfma_f32_16x16x32_bf16 v[98:101], v[200:203], v[154:157], 0
	v_mfma_f32_16x16x32_bf16 v[86:89], v[178:181], v[162:165], 0
	v_mfma_f32_16x16x32_bf16 v[82:85], v[200:203], v[162:165], 0
	v_mfma_f32_16x16x32_bf16 v[70:73], v[178:181], v[170:173], 0
	v_mfma_f32_16x16x32_bf16 v[66:69], v[200:203], v[170:173], 0
	v_mfma_f32_16x16x32_bf16 v[118:121], v[182:185], v[150:153], v[118:121]
	v_mfma_f32_16x16x32_bf16 v[114:117], v[204:207], v[150:153], v[114:117]
	v_mfma_f32_16x16x32_bf16 v[102:105], v[182:185], v[158:161], v[102:105]
	v_mfma_f32_16x16x32_bf16 v[98:101], v[204:207], v[158:161], v[98:101]
	v_mfma_f32_16x16x32_bf16 v[86:89], v[182:185], v[166:169], v[86:89]
	v_mfma_f32_16x16x32_bf16 v[82:85], v[204:207], v[166:169], v[82:85]
	v_mfma_f32_16x16x32_bf16 v[70:73], v[182:185], v[174:177], v[70:73]
	v_mfma_f32_16x16x32_bf16 v[66:69], v[204:207], v[174:177], v[66:69]
	s_mov_b32 m0, s39
	s_barrier
	ds_read_b128 v[146:149], v213 offset:16384
	ds_read_b128 v[150:153], v213 offset:17408
	ds_read_b128 v[154:157], v213 offset:18432
	ds_read_b128 v[158:161], v213 offset:19456
	ds_read_b128 v[162:165], v213 offset:20480
	ds_read_b128 v[166:169], v213 offset:21504
	ds_read_b128 v[170:173], v213 offset:22528
	global_load_lds_dwordx4 v190, s[92:93]
	s_mov_b32 m0, s42
	ds_read_b128 v[174:177], v213 offset:23552
	global_load_lds_dwordx4 v192, s[92:93]
	s_waitcnt vmcnt(10)
	s_barrier
	s_waitcnt lgkmcnt(0)
	v_mfma_f32_16x16x32_bf16 v[62:65], v[130:133], v[146:149], 0
	v_mfma_f32_16x16x32_bf16 v[58:61], v[138:141], v[146:149], 0
	v_mfma_f32_16x16x32_bf16 v[46:49], v[130:133], v[154:157], 0
	v_mfma_f32_16x16x32_bf16 v[42:45], v[138:141], v[154:157], 0
	v_mfma_f32_16x16x32_bf16 v[30:33], v[130:133], v[162:165], 0
	v_mfma_f32_16x16x32_bf16 v[26:29], v[138:141], v[162:165], 0
	v_mfma_f32_16x16x32_bf16 v[14:17], v[130:133], v[170:173], 0
	v_mfma_f32_16x16x32_bf16 v[10:13], v[138:141], v[170:173], 0
	v_mfma_f32_16x16x32_bf16 v[62:65], v[134:137], v[150:153], v[62:65]
	v_mfma_f32_16x16x32_bf16 v[58:61], v[142:145], v[150:153], v[58:61]
	v_mfma_f32_16x16x32_bf16 v[46:49], v[134:137], v[158:161], v[46:49]
	v_mfma_f32_16x16x32_bf16 v[42:45], v[142:145], v[158:161], v[42:45]
	v_mfma_f32_16x16x32_bf16 v[30:33], v[134:137], v[166:169], v[30:33]
	v_mfma_f32_16x16x32_bf16 v[26:29], v[142:145], v[166:169], v[26:29]
	v_mfma_f32_16x16x32_bf16 v[14:17], v[134:137], v[174:177], v[14:17]
	v_mfma_f32_16x16x32_bf16 v[10:13], v[142:145], v[174:177], v[10:13]
	s_barrier
	s_add_u32 s88, s90, 0x40000
	s_addc_u32 s89, s91, 0
	s_add_i32 m0, s38, 0x14000
	s_nop 0
	global_load_lds_dwordx4 v0, s[88:89]
	s_add_i32 m0, s38, 0x16000
	s_nop 0
	global_load_lds_dwordx4 v194, s[88:89]
	s_add_i32 s79, 0, 0x18000
	v_add_u32_e32 v142, s79, v212
	ds_read_b128 v[130:133], v142
	ds_read_b128 v[134:137], v142 offset:1024
	ds_read_b128 v[138:141], v142 offset:2048
	ds_read_b128 v[142:145], v142 offset:3072
	s_waitcnt vmcnt(6)
	s_barrier
	v_mfma_f32_16x16x32_bf16 v[54:57], v[178:181], v[146:149], 0
	v_mfma_f32_16x16x32_bf16 v[50:53], v[200:203], v[146:149], 0
	v_mfma_f32_16x16x32_bf16 v[38:41], v[178:181], v[154:157], 0
	v_mfma_f32_16x16x32_bf16 v[34:37], v[200:203], v[154:157], 0
	v_mfma_f32_16x16x32_bf16 v[22:25], v[178:181], v[162:165], 0
	v_mfma_f32_16x16x32_bf16 v[18:21], v[200:203], v[162:165], 0
	v_mfma_f32_16x16x32_bf16 v[6:9], v[178:181], v[170:173], 0
	v_mfma_f32_16x16x32_bf16 v[2:5], v[200:203], v[170:173], 0
	v_mfma_f32_16x16x32_bf16 v[54:57], v[182:185], v[150:153], v[54:57]
	v_mfma_f32_16x16x32_bf16 v[50:53], v[204:207], v[150:153], v[50:53]
	v_mfma_f32_16x16x32_bf16 v[38:41], v[182:185], v[158:161], v[38:41]
	v_mfma_f32_16x16x32_bf16 v[34:37], v[204:207], v[158:161], v[34:37]
	v_mfma_f32_16x16x32_bf16 v[22:25], v[182:185], v[166:169], v[22:25]
	v_mfma_f32_16x16x32_bf16 v[18:21], v[204:207], v[166:169], v[18:21]
	v_mfma_f32_16x16x32_bf16 v[6:9], v[182:185], v[174:177], v[6:9]
	v_mfma_f32_16x16x32_bf16 v[2:5], v[204:207], v[174:177], v[2:5]
	s_barrier
	s_add_u32 s88, s92, 0xc0000
	s_addc_u32 s89, s93, 0
	s_mov_b32 m0, s43
	ds_read_b128 v[146:149], v213 offset:32768
	ds_read_b128 v[150:153], v213 offset:33792
	ds_read_b128 v[154:157], v213 offset:34816
	ds_read_b128 v[158:161], v213 offset:35840
	ds_read_b128 v[162:165], v213 offset:36864
	ds_read_b128 v[166:169], v213 offset:37888
	ds_read_b128 v[170:173], v213 offset:38912
	global_load_lds_dwordx4 v190, s[88:89]
	s_mov_b32 m0, s44
	ds_read_b128 v[174:177], v213 offset:39936
	global_load_lds_dwordx4 v192, s[88:89]
	s_waitcnt lgkmcnt(8)
	s_barrier
	s_waitcnt lgkmcnt(0)
	v_mfma_f32_16x16x32_bf16 v[126:129], v[130:133], v[146:149], v[126:129]
	v_mfma_f32_16x16x32_bf16 v[122:125], v[138:141], v[146:149], v[122:125]
	v_mfma_f32_16x16x32_bf16 v[110:113], v[130:133], v[154:157], v[110:113]
	v_mfma_f32_16x16x32_bf16 v[106:109], v[138:141], v[154:157], v[106:109]
	v_mfma_f32_16x16x32_bf16 v[94:97], v[130:133], v[162:165], v[94:97]
	v_mfma_f32_16x16x32_bf16 v[90:93], v[138:141], v[162:165], v[90:93]
	v_mfma_f32_16x16x32_bf16 v[78:81], v[130:133], v[170:173], v[78:81]
	v_mfma_f32_16x16x32_bf16 v[74:77], v[138:141], v[170:173], v[74:77]
	v_mfma_f32_16x16x32_bf16 v[126:129], v[134:137], v[150:153], v[126:129]
	v_mfma_f32_16x16x32_bf16 v[122:125], v[142:145], v[150:153], v[122:125]
	v_mfma_f32_16x16x32_bf16 v[110:113], v[134:137], v[158:161], v[110:113]
	v_mfma_f32_16x16x32_bf16 v[106:109], v[142:145], v[158:161], v[106:109]
	v_mfma_f32_16x16x32_bf16 v[94:97], v[134:137], v[166:169], v[94:97]
	v_mfma_f32_16x16x32_bf16 v[90:93], v[142:145], v[166:169], v[90:93]
	v_mfma_f32_16x16x32_bf16 v[78:81], v[134:137], v[174:177], v[78:81]
	v_mfma_f32_16x16x32_bf16 v[74:77], v[142:145], v[174:177], v[74:77]
	s_barrier
	s_add_i32 s87, 0, 0x1c000
	v_add_u32_e32 v204, s87, v212
	s_add_i32 m0, s38, 0x18000
	ds_read_b128 v[178:181], v204
	ds_read_b128 v[182:185], v204 offset:1024
	ds_read_b128 v[200:203], v204 offset:2048
	ds_read_b128 v[204:207], v204 offset:3072
	s_add_u32 s98, s90, s40
	s_addc_u32 s99, s91, s41
	global_load_lds_dwordx4 v0, s[98:99]
	s_add_i32 m0, s38, 0x1a000
	s_nop 0
	global_load_lds_dwordx4 v194, s[98:99]
	s_barrier
	s_waitcnt lgkmcnt(0)
	v_mfma_f32_16x16x32_bf16 v[118:121], v[178:181], v[146:149], v[118:121]
	v_mfma_f32_16x16x32_bf16 v[114:117], v[200:203], v[146:149], v[114:117]
	v_mfma_f32_16x16x32_bf16 v[102:105], v[178:181], v[154:157], v[102:105]
	v_mfma_f32_16x16x32_bf16 v[98:101], v[200:203], v[154:157], v[98:101]
	v_mfma_f32_16x16x32_bf16 v[86:89], v[178:181], v[162:165], v[86:89]
	v_mfma_f32_16x16x32_bf16 v[82:85], v[200:203], v[162:165], v[82:85]
	v_mfma_f32_16x16x32_bf16 v[70:73], v[178:181], v[170:173], v[70:73]
	v_mfma_f32_16x16x32_bf16 v[66:69], v[200:203], v[170:173], v[66:69]
	v_mfma_f32_16x16x32_bf16 v[118:121], v[182:185], v[150:153], v[118:121]
	v_mfma_f32_16x16x32_bf16 v[114:117], v[204:207], v[150:153], v[114:117]
	v_mfma_f32_16x16x32_bf16 v[102:105], v[182:185], v[158:161], v[102:105]
	v_mfma_f32_16x16x32_bf16 v[98:101], v[204:207], v[158:161], v[98:101]
	v_mfma_f32_16x16x32_bf16 v[86:89], v[182:185], v[166:169], v[86:89]
	v_mfma_f32_16x16x32_bf16 v[82:85], v[204:207], v[166:169], v[82:85]
	v_mfma_f32_16x16x32_bf16 v[70:73], v[182:185], v[174:177], v[70:73]
	v_mfma_f32_16x16x32_bf16 v[66:69], v[204:207], v[174:177], v[66:69]
	s_mov_b32 m0, s60
	s_barrier
	ds_read_b128 v[146:149], v213 offset:49152
	ds_read_b128 v[150:153], v213 offset:50176
	ds_read_b128 v[154:157], v213 offset:51200
	ds_read_b128 v[158:161], v213 offset:52224
	ds_read_b128 v[162:165], v213 offset:53248
	ds_read_b128 v[166:169], v213 offset:54272
	ds_read_b128 v[170:173], v213 offset:55296
	ds_read_b128 v[174:177], v213 offset:56320
	s_add_u32 s98, s92, s40
	s_addc_u32 s99, s93, s41
	global_load_lds_dwordx4 v190, s[98:99]
	s_mov_b32 m0, s61
	s_nop 0
	global_load_lds_dwordx4 v192, s[98:99]
	s_waitcnt vmcnt(10)
	s_barrier
	s_waitcnt lgkmcnt(0)
	v_mfma_f32_16x16x32_bf16 v[62:65], v[130:133], v[146:149], v[62:65]
	v_mfma_f32_16x16x32_bf16 v[58:61], v[138:141], v[146:149], v[58:61]
	v_mfma_f32_16x16x32_bf16 v[46:49], v[130:133], v[154:157], v[46:49]
	v_mfma_f32_16x16x32_bf16 v[42:45], v[138:141], v[154:157], v[42:45]
	v_mfma_f32_16x16x32_bf16 v[30:33], v[130:133], v[162:165], v[30:33]
	v_mfma_f32_16x16x32_bf16 v[26:29], v[138:141], v[162:165], v[26:29]
	v_mfma_f32_16x16x32_bf16 v[14:17], v[130:133], v[170:173], v[14:17]
	v_mfma_f32_16x16x32_bf16 v[10:13], v[138:141], v[170:173], v[10:13]
	v_mfma_f32_16x16x32_bf16 v[62:65], v[134:137], v[150:153], v[62:65]
	v_mfma_f32_16x16x32_bf16 v[58:61], v[142:145], v[150:153], v[58:61]
	v_mfma_f32_16x16x32_bf16 v[46:49], v[134:137], v[158:161], v[46:49]
	v_mfma_f32_16x16x32_bf16 v[42:45], v[142:145], v[158:161], v[42:45]
	v_mfma_f32_16x16x32_bf16 v[30:33], v[134:137], v[166:169], v[30:33]
	v_mfma_f32_16x16x32_bf16 v[26:29], v[142:145], v[166:169], v[26:29]
	v_mfma_f32_16x16x32_bf16 v[14:17], v[134:137], v[174:177], v[14:17]
	v_mfma_f32_16x16x32_bf16 v[10:13], v[142:145], v[174:177], v[10:13]
	s_barrier
	s_add_u32 s88, s90, 0x40080
	s_addc_u32 s89, s91, 0
	s_add_i32 m0, s38, 0x1c000
	s_nop 0
	global_load_lds_dwordx4 v0, s[88:89]
	s_add_i32 m0, s38, 0x1e000
	s_nop 0
	global_load_lds_dwordx4 v194, s[88:89]
	ds_read_b128 v[130:133], v189
	ds_read_b128 v[134:137], v189 offset:1024
	ds_read_b128 v[138:141], v189 offset:2048
	ds_read_b128 v[142:145], v189 offset:3072
	s_waitcnt vmcnt(6)
	s_barrier
	v_mfma_f32_16x16x32_bf16 v[54:57], v[178:181], v[146:149], v[54:57]
	v_mfma_f32_16x16x32_bf16 v[50:53], v[200:203], v[146:149], v[50:53]
	v_mfma_f32_16x16x32_bf16 v[38:41], v[178:181], v[154:157], v[38:41]
	v_mfma_f32_16x16x32_bf16 v[34:37], v[200:203], v[154:157], v[34:37]
	v_mfma_f32_16x16x32_bf16 v[22:25], v[178:181], v[162:165], v[22:25]
	v_mfma_f32_16x16x32_bf16 v[18:21], v[200:203], v[162:165], v[18:21]
	v_mfma_f32_16x16x32_bf16 v[6:9], v[178:181], v[170:173], v[6:9]
	v_mfma_f32_16x16x32_bf16 v[2:5], v[200:203], v[170:173], v[2:5]
	v_mfma_f32_16x16x32_bf16 v[54:57], v[182:185], v[150:153], v[54:57]
	v_mfma_f32_16x16x32_bf16 v[50:53], v[204:207], v[150:153], v[50:53]
	v_mfma_f32_16x16x32_bf16 v[38:41], v[182:185], v[158:161], v[38:41]
	v_mfma_f32_16x16x32_bf16 v[34:37], v[204:207], v[158:161], v[34:37]
	v_mfma_f32_16x16x32_bf16 v[22:25], v[182:185], v[166:169], v[22:25]
	v_mfma_f32_16x16x32_bf16 v[18:21], v[204:207], v[166:169], v[18:21]
	v_mfma_f32_16x16x32_bf16 v[6:9], v[182:185], v[174:177], v[6:9]
	v_mfma_f32_16x16x32_bf16 v[2:5], v[204:207], v[174:177], v[2:5]
	s_add_i32 s78, s78, 2
	s_add_u32 s34, s34, 0x100
	s_addc_u32 s75, s75, 0
	s_mov_b64 s[88:89], s[4:5]
	s_add_u32 s4, s88, 0x100
	s_addc_u32 s5, s89, 0
	s_cmp_eq_u32 s78, 12
	s_cselect_b32 s93, s17, s5
	s_cselect_b32 s92, s16, s4
	s_cselect_b32 s91, s15, s75
	s_cselect_b32 s90, s23, s34
	s_cmp_gt_u32 s78, 13
	s_barrier
	.p2align 3

.LBB0_918:
	s_ashr_i32 s17, s16, 31
	s_lshl_b64 s[22:23], s[16:17], 19
	v_mov_b64_e32 v[2:3], 0xb00
	s_add_u32 s84, s8, s22
	v_cmp_lt_i64_e32 vcc, s[28:29], v[2:3]
	s_addc_u32 s85, s9, s23
	s_and_b64 s[22:23], vcc, exec
	s_cselect_b32 s17, s85, s7
	s_cselect_b32 s22, s84, s6
	s_ashr_i32 s15, s14, 31
	s_lshl_b64 s[28:29], s[14:15], 19
	s_add_u32 s86, s37, s28
	s_addc_u32 s87, s38, s29
	s_and_b64 s[28:29], vcc, exec
	s_cselect_b32 s15, s87, s89
	s_cselect_b32 s23, s86, s88
	s_add_u32 s28, s88, 0x100
	s_addc_u32 s29, s89, 0
	s_mov_b32 s45, -2
	s_add_i32 vcc_lo, 0, 0x10000
	v_add_u32_e32 v0, vcc_lo, v254
	v_add_u32_e32 v189, 0x10000, v254
	ds_read_b128 v[130:133], v0
	ds_read_b128 v[134:137], v0 offset:1024
	ds_read_b128 v[138:141], v0 offset:2048
	ds_read_b128 v[142:145], v0 offset:3072
	s_add_u32 s88, s6, 0x100
	s_addc_u32 s89, s7, 0
	s_cmp_eq_u32 s45, 12
	s_cselect_b32 s93, s17, s89
	s_cselect_b32 s92, s22, s88
	s_cselect_b32 s91, s15, s29
	s_cselect_b32 s90, s23, s28
	s_add_i32 m0, s43, 0xc000
	ds_read_b128 v[146:149], v253
	ds_read_b128 v[150:153], v253 offset:1024
	ds_read_b128 v[168:171], v253 offset:2048
	ds_read_b128 v[172:175], v253 offset:3072
	ds_read_b128 v[176:179], v253 offset:4096
	ds_read_b128 v[180:183], v253 offset:5120
	ds_read_b128 v[184:187], v253 offset:6144
	ds_read_b128 v[190:193], v253 offset:7168
	global_load_lds_dwordx4 v164, s[6:7]
	s_add_i32 m0, s43, 0xe000
	v_lshl_add_u64 v[154:155], s[6:7], 0, v[166:167]
	global_load_lds_dwordx4 v[154:155], off
	s_waitcnt lgkmcnt(8)
	s_barrier
	s_waitcnt lgkmcnt(0)
	v_mfma_f32_16x16x32_bf16 v[126:129], v[130:133], v[146:149], 0
	v_mfma_f32_16x16x32_bf16 v[70:73], v[138:141], v[146:149], 0
	v_mfma_f32_16x16x32_bf16 v[122:125], v[130:133], v[168:171], 0
	v_mfma_f32_16x16x32_bf16 v[74:77], v[138:141], v[168:171], 0
	v_mfma_f32_16x16x32_bf16 v[114:117], v[130:133], v[176:179], 0
	v_mfma_f32_16x16x32_bf16 v[66:69], v[138:141], v[176:179], 0
	v_mfma_f32_16x16x32_bf16 v[110:113], v[130:133], v[184:187], 0
	v_mfma_f32_16x16x32_bf16 v[78:81], v[138:141], v[184:187], 0
	v_mfma_f32_16x16x32_bf16 v[126:129], v[134:137], v[150:153], v[126:129]
	v_mfma_f32_16x16x32_bf16 v[70:73], v[142:145], v[150:153], v[70:73]
	v_mfma_f32_16x16x32_bf16 v[122:125], v[134:137], v[172:175], v[122:125]
	v_mfma_f32_16x16x32_bf16 v[74:77], v[142:145], v[172:175], v[74:77]
	v_mfma_f32_16x16x32_bf16 v[114:117], v[134:137], v[180:183], v[114:117]
	v_mfma_f32_16x16x32_bf16 v[66:69], v[142:145], v[180:183], v[66:69]
	v_mfma_f32_16x16x32_bf16 v[110:113], v[134:137], v[190:193], v[110:113]
	v_mfma_f32_16x16x32_bf16 v[78:81], v[142:145], v[190:193], v[78:81]
	s_barrier
	s_add_i32 m0, s39, 0x10000
	ds_read_b128 v[194:197], v189 offset:16384
	ds_read_b128 v[198:201], v189 offset:17408
	ds_read_b128 v[202:205], v189 offset:18432
	global_load_lds_dwordx4 v160, s[90:91]
	s_add_i32 m0, s39, 0x12000
	ds_read_b128 v[206:209], v189 offset:19456
	global_load_lds_dwordx4 v156, s[90:91]
	s_barrier
	s_waitcnt lgkmcnt(0)
	v_mfma_f32_16x16x32_bf16 v[118:121], v[194:197], v[146:149], 0
	v_mfma_f32_16x16x32_bf16 v[94:97], v[202:205], v[146:149], 0
	v_mfma_f32_16x16x32_bf16 v[106:109], v[194:197], v[168:171], 0
	v_mfma_f32_16x16x32_bf16 v[90:93], v[202:205], v[168:171], 0
	v_mfma_f32_16x16x32_bf16 v[102:105], v[194:197], v[176:179], 0
	v_mfma_f32_16x16x32_bf16 v[82:85], v[202:205], v[176:179], 0
	v_mfma_f32_16x16x32_bf16 v[98:101], v[194:197], v[184:187], 0
	v_mfma_f32_16x16x32_bf16 v[86:89], v[202:205], v[184:187], 0
	v_mfma_f32_16x16x32_bf16 v[118:121], v[198:201], v[150:153], v[118:121]
	v_mfma_f32_16x16x32_bf16 v[94:97], v[206:209], v[150:153], v[94:97]
	v_mfma_f32_16x16x32_bf16 v[106:109], v[198:201], v[172:175], v[106:109]
	v_mfma_f32_16x16x32_bf16 v[90:93], v[206:209], v[172:175], v[90:93]
	v_mfma_f32_16x16x32_bf16 v[102:105], v[198:201], v[180:183], v[102:105]
	v_mfma_f32_16x16x32_bf16 v[82:85], v[206:209], v[180:183], v[82:85]
	v_mfma_f32_16x16x32_bf16 v[98:101], v[198:201], v[190:193], v[98:101]
	v_mfma_f32_16x16x32_bf16 v[86:89], v[206:209], v[190:193], v[86:89]
	s_mov_b32 m0, s43
	s_mov_b64 s[100:101], s[92:93]
	s_barrier
	ds_read_b128 v[146:149], v253 offset:16384
	ds_read_b128 v[150:153], v253 offset:17408
	ds_read_b128 v[168:171], v253 offset:18432
	ds_read_b128 v[172:175], v253 offset:19456
	ds_read_b128 v[176:179], v253 offset:20480
	ds_read_b128 v[180:183], v253 offset:21504
	ds_read_b128 v[184:187], v253 offset:22528
	global_load_lds_dwordx4 v162, s[100:101]
	s_mov_b32 m0, s60
	ds_read_b128 v[190:193], v253 offset:23552
	global_load_lds_dwordx4 v158, s[100:101]
	s_waitcnt vmcnt(10)
	s_barrier
	s_waitcnt lgkmcnt(0)
	v_mfma_f32_16x16x32_bf16 v[62:65], v[130:133], v[146:149], 0
	v_mfma_f32_16x16x32_bf16 v[10:13], v[138:141], v[146:149], 0
	v_mfma_f32_16x16x32_bf16 v[58:61], v[130:133], v[168:171], 0
	v_mfma_f32_16x16x32_bf16 v[14:17], v[138:141], v[168:171], 0
	v_mfma_f32_16x16x32_bf16 v[54:57], v[130:133], v[176:179], 0
	v_mfma_f32_16x16x32_bf16 v[6:9], v[138:141], v[176:179], 0
	v_mfma_f32_16x16x32_bf16 v[42:45], v[130:133], v[184:187], 0
	v_mfma_f32_16x16x32_bf16 v[2:5], v[138:141], v[184:187], 0
	v_mfma_f32_16x16x32_bf16 v[62:65], v[134:137], v[150:153], v[62:65]
	v_mfma_f32_16x16x32_bf16 v[10:13], v[142:145], v[150:153], v[10:13]
	v_mfma_f32_16x16x32_bf16 v[58:61], v[134:137], v[172:175], v[58:61]
	v_mfma_f32_16x16x32_bf16 v[14:17], v[142:145], v[172:175], v[14:17]
	v_mfma_f32_16x16x32_bf16 v[54:57], v[134:137], v[180:183], v[54:57]
	v_mfma_f32_16x16x32_bf16 v[6:9], v[142:145], v[180:183], v[6:9]
	v_mfma_f32_16x16x32_bf16 v[42:45], v[134:137], v[190:193], v[42:45]
	v_mfma_f32_16x16x32_bf16 v[2:5], v[142:145], v[190:193], v[2:5]
	s_barrier
	s_add_u32 s6, s90, 0x40000
	s_addc_u32 s7, s91, 0
	s_add_i32 m0, s39, 0x14000
	s_nop 0
	global_load_lds_dwordx4 v160, s[6:7]
	s_add_i32 m0, s39, 0x16000
	s_nop 0
	global_load_lds_dwordx4 v156, s[6:7]
	ds_read_b128 v[130:133], v189 offset:32768
	ds_read_b128 v[134:137], v189 offset:33792
	ds_read_b128 v[138:141], v189 offset:34816
	ds_read_b128 v[142:145], v189 offset:35840
	s_waitcnt vmcnt(6)
	s_barrier
	v_mfma_f32_16x16x32_bf16 v[50:53], v[194:197], v[146:149], 0
	v_mfma_f32_16x16x32_bf16 v[26:29], v[202:205], v[146:149], 0
	v_mfma_f32_16x16x32_bf16 v[46:49], v[194:197], v[168:171], 0
	v_mfma_f32_16x16x32_bf16 v[30:33], v[202:205], v[168:171], 0
	v_mfma_f32_16x16x32_bf16 v[38:41], v[194:197], v[176:179], 0
	v_mfma_f32_16x16x32_bf16 v[22:25], v[202:205], v[176:179], 0
	v_mfma_f32_16x16x32_bf16 v[34:37], v[194:197], v[184:187], 0
	v_mfma_f32_16x16x32_bf16 v[18:21], v[202:205], v[184:187], 0
	v_mfma_f32_16x16x32_bf16 v[50:53], v[198:201], v[150:153], v[50:53]
	v_mfma_f32_16x16x32_bf16 v[26:29], v[206:209], v[150:153], v[26:29]
	v_mfma_f32_16x16x32_bf16 v[46:49], v[198:201], v[172:175], v[46:49]
	v_mfma_f32_16x16x32_bf16 v[30:33], v[206:209], v[172:175], v[30:33]
	v_mfma_f32_16x16x32_bf16 v[38:41], v[198:201], v[180:183], v[38:41]
	v_mfma_f32_16x16x32_bf16 v[22:25], v[206:209], v[180:183], v[22:25]
	v_mfma_f32_16x16x32_bf16 v[34:37], v[198:201], v[190:193], v[34:37]
	v_mfma_f32_16x16x32_bf16 v[18:21], v[206:209], v[190:193], v[18:21]
	s_barrier
	s_add_u32 s6, s92, 0x40000
	s_addc_u32 s7, s93, 0
	s_mov_b32 m0, s61
	ds_read_b128 v[146:149], v253 offset:32768
	ds_read_b128 v[150:153], v253 offset:33792
	ds_read_b128 v[168:171], v253 offset:34816
	ds_read_b128 v[172:175], v253 offset:35840
	ds_read_b128 v[176:179], v253 offset:36864
	ds_read_b128 v[180:183], v253 offset:37888
	ds_read_b128 v[184:187], v253 offset:38912
	global_load_lds_dwordx4 v162, s[6:7]
	s_mov_b32 m0, s72
	ds_read_b128 v[190:193], v253 offset:39936
	global_load_lds_dwordx4 v158, s[6:7]
	s_waitcnt lgkmcnt(8)
	s_barrier
	s_waitcnt lgkmcnt(0)
	v_mfma_f32_16x16x32_bf16 v[126:129], v[130:133], v[146:149], v[126:129]
	v_mfma_f32_16x16x32_bf16 v[70:73], v[138:141], v[146:149], v[70:73]
	v_mfma_f32_16x16x32_bf16 v[122:125], v[130:133], v[168:171], v[122:125]
	v_mfma_f32_16x16x32_bf16 v[74:77], v[138:141], v[168:171], v[74:77]
	v_mfma_f32_16x16x32_bf16 v[114:117], v[130:133], v[176:179], v[114:117]
	v_mfma_f32_16x16x32_bf16 v[66:69], v[138:141], v[176:179], v[66:69]
	v_mfma_f32_16x16x32_bf16 v[110:113], v[130:133], v[184:187], v[110:113]
	v_mfma_f32_16x16x32_bf16 v[78:81], v[138:141], v[184:187], v[78:81]
	v_mfma_f32_16x16x32_bf16 v[126:129], v[134:137], v[150:153], v[126:129]
	v_mfma_f32_16x16x32_bf16 v[70:73], v[142:145], v[150:153], v[70:73]
	v_mfma_f32_16x16x32_bf16 v[122:125], v[134:137], v[172:175], v[122:125]
	v_mfma_f32_16x16x32_bf16 v[74:77], v[142:145], v[172:175], v[74:77]
	v_mfma_f32_16x16x32_bf16 v[114:117], v[134:137], v[180:183], v[114:117]
	v_mfma_f32_16x16x32_bf16 v[66:69], v[142:145], v[180:183], v[66:69]
	v_mfma_f32_16x16x32_bf16 v[110:113], v[134:137], v[190:193], v[110:113]
	v_mfma_f32_16x16x32_bf16 v[78:81], v[142:145], v[190:193], v[78:81]
	s_barrier
	s_add_i32 m0, s39, 0x18000
	ds_read_b128 v[194:197], v189 offset:49152
	ds_read_b128 v[198:201], v189 offset:50176
	ds_read_b128 v[202:205], v189 offset:51200
	ds_read_b128 v[206:209], v189 offset:52224
	s_add_u32 s98, s90, s40
	s_addc_u32 s99, s91, s41
	global_load_lds_dwordx4 v160, s[98:99]
	s_add_i32 m0, s39, 0x1a000
	s_nop 0
	global_load_lds_dwordx4 v156, s[98:99]
	s_barrier
	s_waitcnt lgkmcnt(0)
	v_mfma_f32_16x16x32_bf16 v[118:121], v[194:197], v[146:149], v[118:121]
	v_mfma_f32_16x16x32_bf16 v[94:97], v[202:205], v[146:149], v[94:97]
	v_mfma_f32_16x16x32_bf16 v[106:109], v[194:197], v[168:171], v[106:109]
	v_mfma_f32_16x16x32_bf16 v[90:93], v[202:205], v[168:171], v[90:93]
	v_mfma_f32_16x16x32_bf16 v[102:105], v[194:197], v[176:179], v[102:105]
	v_mfma_f32_16x16x32_bf16 v[82:85], v[202:205], v[176:179], v[82:85]
	v_mfma_f32_16x16x32_bf16 v[98:101], v[194:197], v[184:187], v[98:101]
	v_mfma_f32_16x16x32_bf16 v[86:89], v[202:205], v[184:187], v[86:89]
	v_mfma_f32_16x16x32_bf16 v[118:121], v[198:201], v[150:153], v[118:121]
	v_mfma_f32_16x16x32_bf16 v[94:97], v[206:209], v[150:153], v[94:97]
	v_mfma_f32_16x16x32_bf16 v[106:109], v[198:201], v[172:175], v[106:109]
	v_mfma_f32_16x16x32_bf16 v[90:93], v[206:209], v[172:175], v[90:93]
	v_mfma_f32_16x16x32_bf16 v[102:105], v[198:201], v[180:183], v[102:105]
	v_mfma_f32_16x16x32_bf16 v[82:85], v[206:209], v[180:183], v[82:85]
	v_mfma_f32_16x16x32_bf16 v[98:101], v[198:201], v[190:193], v[98:101]
	v_mfma_f32_16x16x32_bf16 v[86:89], v[206:209], v[190:193], v[86:89]
	s_mov_b32 m0, s95
	s_barrier
	ds_read_b128 v[146:149], v253 offset:49152
	ds_read_b128 v[150:153], v253 offset:50176
	ds_read_b128 v[168:171], v253 offset:51200
	ds_read_b128 v[172:175], v253 offset:52224
	ds_read_b128 v[176:179], v253 offset:53248
	ds_read_b128 v[180:183], v253 offset:54272
	ds_read_b128 v[184:187], v253 offset:55296
	ds_read_b128 v[190:193], v253 offset:56320
	s_add_u32 s98, s100, s40
	s_addc_u32 s99, s101, s41
	global_load_lds_dwordx4 v162, s[98:99]
	s_mov_b32 m0, s96
	s_nop 0
	global_load_lds_dwordx4 v158, s[98:99]
	s_waitcnt vmcnt(10)
	s_barrier
	s_waitcnt lgkmcnt(0)
	v_mfma_f32_16x16x32_bf16 v[62:65], v[130:133], v[146:149], v[62:65]
	v_mfma_f32_16x16x32_bf16 v[10:13], v[138:141], v[146:149], v[10:13]
	v_mfma_f32_16x16x32_bf16 v[58:61], v[130:133], v[168:171], v[58:61]
	v_mfma_f32_16x16x32_bf16 v[14:17], v[138:141], v[168:171], v[14:17]
	v_mfma_f32_16x16x32_bf16 v[54:57], v[130:133], v[176:179], v[54:57]
	v_mfma_f32_16x16x32_bf16 v[6:9], v[138:141], v[176:179], v[6:9]
	v_mfma_f32_16x16x32_bf16 v[42:45], v[130:133], v[184:187], v[42:45]
	v_mfma_f32_16x16x32_bf16 v[2:5], v[138:141], v[184:187], v[2:5]
	v_mfma_f32_16x16x32_bf16 v[62:65], v[134:137], v[150:153], v[62:65]
	v_mfma_f32_16x16x32_bf16 v[10:13], v[142:145], v[150:153], v[10:13]
	v_mfma_f32_16x16x32_bf16 v[58:61], v[134:137], v[172:175], v[58:61]
	v_mfma_f32_16x16x32_bf16 v[14:17], v[142:145], v[172:175], v[14:17]
	v_mfma_f32_16x16x32_bf16 v[54:57], v[134:137], v[180:183], v[54:57]
	v_mfma_f32_16x16x32_bf16 v[6:9], v[142:145], v[180:183], v[6:9]
	v_mfma_f32_16x16x32_bf16 v[42:45], v[134:137], v[190:193], v[42:45]
	v_mfma_f32_16x16x32_bf16 v[2:5], v[142:145], v[190:193], v[2:5]
	s_barrier
	s_add_u32 s6, s90, 0x40080
	s_addc_u32 s7, s91, 0
	s_add_i32 m0, s39, 0x1c000
	s_nop 0
	global_load_lds_dwordx4 v160, s[6:7]
	s_add_i32 m0, s39, 0x1e000
	s_nop 0
	global_load_lds_dwordx4 v156, s[6:7]
	ds_read_b128 v[130:133], v189
	ds_read_b128 v[134:137], v189 offset:1024
	ds_read_b128 v[138:141], v189 offset:2048
	ds_read_b128 v[142:145], v189 offset:3072
	s_waitcnt vmcnt(6)
	s_barrier
	v_mfma_f32_16x16x32_bf16 v[50:53], v[194:197], v[146:149], v[50:53]
	v_mfma_f32_16x16x32_bf16 v[26:29], v[202:205], v[146:149], v[26:29]
	v_mfma_f32_16x16x32_bf16 v[46:49], v[194:197], v[168:171], v[46:49]
	v_mfma_f32_16x16x32_bf16 v[30:33], v[202:205], v[168:171], v[30:33]
	v_mfma_f32_16x16x32_bf16 v[38:41], v[194:197], v[176:179], v[38:41]
	v_mfma_f32_16x16x32_bf16 v[22:25], v[202:205], v[176:179], v[22:25]
	v_mfma_f32_16x16x32_bf16 v[34:37], v[194:197], v[184:187], v[34:37]
	v_mfma_f32_16x16x32_bf16 v[18:21], v[202:205], v[184:187], v[18:21]
	v_mfma_f32_16x16x32_bf16 v[50:53], v[198:201], v[150:153], v[50:53]
	v_mfma_f32_16x16x32_bf16 v[26:29], v[206:209], v[150:153], v[26:29]
	v_mfma_f32_16x16x32_bf16 v[46:49], v[198:201], v[172:175], v[46:49]
	v_mfma_f32_16x16x32_bf16 v[30:33], v[206:209], v[172:175], v[30:33]
	v_mfma_f32_16x16x32_bf16 v[38:41], v[198:201], v[180:183], v[38:41]
	v_mfma_f32_16x16x32_bf16 v[22:25], v[206:209], v[180:183], v[22:25]
	v_mfma_f32_16x16x32_bf16 v[34:37], v[198:201], v[190:193], v[34:37]
	v_mfma_f32_16x16x32_bf16 v[18:21], v[206:209], v[190:193], v[18:21]
	s_add_i32 s45, s45, 2
	s_add_u32 s28, s28, 0x100
	s_addc_u32 s29, s29, 0
	s_mov_b64 s[6:7], s[88:89]
	s_add_u32 s88, s6, 0x100
	s_addc_u32 s89, s7, 0
	s_cmp_eq_u32 s45, 12
	s_cselect_b32 s93, s17, s89
	s_cselect_b32 s92, s22, s88
	s_cselect_b32 s91, s15, s29
	s_cselect_b32 s90, s23, s28
	s_cmp_gt_u32 s45, 13
	s_barrier
	.p2align 3

.LBB0_1089:
	s_add_u32 s34, s84, 0x100
	s_addc_u32 s78, s85, 0
	s_mov_b32 s79, -2
	s_waitcnt lgkmcnt(0)
	s_add_i32 s90, 0, 0x10000
	v_add_u32_e32 v142, s90, v212
	v_add_u32_e32 v189, 0x10000, v212
	ds_read_b128 v[130:133], v142
	ds_read_b128 v[134:137], v142 offset:1024
	ds_read_b128 v[138:141], v142 offset:2048
	ds_read_b128 v[142:145], v142 offset:3072
	s_add_u32 s84, s16, 0x100
	s_addc_u32 s85, s17, 0
	s_cmp_eq_u32 s79, 40
	s_cselect_b32 s89, s5, s85
	s_cselect_b32 s88, s4, s84
	s_cselect_b32 s87, s7, s78
	s_cselect_b32 s86, s6, s34
	v_lshl_add_u64 v[178:179], s[16:17], 0, v[196:197]
	s_add_i32 m0, s39, 0xc000
	ds_read_b128 v[146:149], v213
	ds_read_b128 v[150:153], v213 offset:1024
	ds_read_b128 v[154:157], v213 offset:2048
	ds_read_b128 v[158:161], v213 offset:3072
	ds_read_b128 v[162:165], v213 offset:4096
	ds_read_b128 v[166:169], v213 offset:5120
	ds_read_b128 v[170:173], v213 offset:6144
	ds_read_b128 v[174:177], v213 offset:7168
	global_load_lds_dwordx4 v[178:179], off
	s_add_i32 m0, s39, 0xe000
	v_lshl_add_u64 v[178:179], s[16:17], 0, v[198:199]
	global_load_lds_dwordx4 v[178:179], off
	s_waitcnt lgkmcnt(8)
	s_barrier
	s_waitcnt lgkmcnt(0)
	v_mfma_f32_16x16x32_bf16 v[126:129], v[130:133], v[146:149], 0
	v_mfma_f32_16x16x32_bf16 v[122:125], v[138:141], v[146:149], 0
	v_mfma_f32_16x16x32_bf16 v[110:113], v[130:133], v[154:157], 0
	v_mfma_f32_16x16x32_bf16 v[106:109], v[138:141], v[154:157], 0
	v_mfma_f32_16x16x32_bf16 v[94:97], v[130:133], v[162:165], 0
	v_mfma_f32_16x16x32_bf16 v[90:93], v[138:141], v[162:165], 0
	v_mfma_f32_16x16x32_bf16 v[78:81], v[130:133], v[170:173], 0
	v_mfma_f32_16x16x32_bf16 v[74:77], v[138:141], v[170:173], 0
	v_mfma_f32_16x16x32_bf16 v[126:129], v[134:137], v[150:153], v[126:129]
	v_mfma_f32_16x16x32_bf16 v[122:125], v[142:145], v[150:153], v[122:125]
	v_mfma_f32_16x16x32_bf16 v[110:113], v[134:137], v[158:161], v[110:113]
	v_mfma_f32_16x16x32_bf16 v[106:109], v[142:145], v[158:161], v[106:109]
	v_mfma_f32_16x16x32_bf16 v[94:97], v[134:137], v[166:169], v[94:97]
	v_mfma_f32_16x16x32_bf16 v[90:93], v[142:145], v[166:169], v[90:93]
	v_mfma_f32_16x16x32_bf16 v[78:81], v[134:137], v[174:177], v[78:81]
	v_mfma_f32_16x16x32_bf16 v[74:77], v[142:145], v[174:177], v[74:77]
	s_barrier
	ds_read_b128 v[178:181], v189 offset:16384
	ds_read_b128 v[182:185], v189 offset:17408
	ds_read_b128 v[200:203], v189 offset:18432
	ds_read_b128 v[204:207], v189 offset:19456
	s_add_i32 m0, s38, 0x10000
	s_nop 0
	global_load_lds_dwordx4 v0, s[86:87]
	s_add_i32 m0, s38, 0x12000
	s_nop 0
	global_load_lds_dwordx4 v194, s[86:87]
	s_barrier
	s_waitcnt lgkmcnt(0)
	v_mfma_f32_16x16x32_bf16 v[118:121], v[178:181], v[146:149], 0
	v_mfma_f32_16x16x32_bf16 v[114:117], v[200:203], v[146:149], 0
	v_mfma_f32_16x16x32_bf16 v[102:105], v[178:181], v[154:157], 0
	v_mfma_f32_16x16x32_bf16 v[98:101], v[200:203], v[154:157], 0
	v_mfma_f32_16x16x32_bf16 v[86:89], v[178:181], v[162:165], 0
	v_mfma_f32_16x16x32_bf16 v[82:85], v[200:203], v[162:165], 0
	v_mfma_f32_16x16x32_bf16 v[70:73], v[178:181], v[170:173], 0
	v_mfma_f32_16x16x32_bf16 v[66:69], v[200:203], v[170:173], 0
	v_mfma_f32_16x16x32_bf16 v[118:121], v[182:185], v[150:153], v[118:121]
	v_mfma_f32_16x16x32_bf16 v[114:117], v[204:207], v[150:153], v[114:117]
	v_mfma_f32_16x16x32_bf16 v[102:105], v[182:185], v[158:161], v[102:105]
	v_mfma_f32_16x16x32_bf16 v[98:101], v[204:207], v[158:161], v[98:101]
	v_mfma_f32_16x16x32_bf16 v[86:89], v[182:185], v[166:169], v[86:89]
	v_mfma_f32_16x16x32_bf16 v[82:85], v[204:207], v[166:169], v[82:85]
	v_mfma_f32_16x16x32_bf16 v[70:73], v[182:185], v[174:177], v[70:73]
	v_mfma_f32_16x16x32_bf16 v[66:69], v[204:207], v[174:177], v[66:69]
	s_mov_b32 m0, s39
	s_mov_b64 s[100:101], s[88:89]
	s_barrier
	ds_read_b128 v[146:149], v213 offset:16384
	ds_read_b128 v[150:153], v213 offset:17408
	ds_read_b128 v[154:157], v213 offset:18432
	ds_read_b128 v[158:161], v213 offset:19456
	ds_read_b128 v[162:165], v213 offset:20480
	ds_read_b128 v[166:169], v213 offset:21504
	ds_read_b128 v[170:173], v213 offset:22528
	global_load_lds_dwordx4 v190, s[100:101]
	s_mov_b32 m0, s42
	ds_read_b128 v[174:177], v213 offset:23552
	global_load_lds_dwordx4 v192, s[100:101]
	s_waitcnt vmcnt(10)
	s_barrier
	s_waitcnt lgkmcnt(0)
	v_mfma_f32_16x16x32_bf16 v[62:65], v[130:133], v[146:149], 0
	v_mfma_f32_16x16x32_bf16 v[58:61], v[138:141], v[146:149], 0
	v_mfma_f32_16x16x32_bf16 v[46:49], v[130:133], v[154:157], 0
	v_mfma_f32_16x16x32_bf16 v[42:45], v[138:141], v[154:157], 0
	v_mfma_f32_16x16x32_bf16 v[30:33], v[130:133], v[162:165], 0
	v_mfma_f32_16x16x32_bf16 v[26:29], v[138:141], v[162:165], 0
	v_mfma_f32_16x16x32_bf16 v[14:17], v[130:133], v[170:173], 0
	v_mfma_f32_16x16x32_bf16 v[10:13], v[138:141], v[170:173], 0
	v_mfma_f32_16x16x32_bf16 v[62:65], v[134:137], v[150:153], v[62:65]
	v_mfma_f32_16x16x32_bf16 v[58:61], v[142:145], v[150:153], v[58:61]
	v_mfma_f32_16x16x32_bf16 v[46:49], v[134:137], v[158:161], v[46:49]
	v_mfma_f32_16x16x32_bf16 v[42:45], v[142:145], v[158:161], v[42:45]
	v_mfma_f32_16x16x32_bf16 v[30:33], v[134:137], v[166:169], v[30:33]
	v_mfma_f32_16x16x32_bf16 v[26:29], v[142:145], v[166:169], v[26:29]
	v_mfma_f32_16x16x32_bf16 v[14:17], v[134:137], v[174:177], v[14:17]
	v_mfma_f32_16x16x32_bf16 v[10:13], v[142:145], v[174:177], v[10:13]
	s_barrier
	s_add_u32 s16, s86, 0xb0000
	s_addc_u32 s17, s87, 0
	s_add_i32 m0, s38, 0x14000
	s_nop 0
	global_load_lds_dwordx4 v0, s[16:17]
	s_add_i32 m0, s38, 0x16000
	s_nop 0
	global_load_lds_dwordx4 v194, s[16:17]
	s_add_i32 s90, 0, 0x18000
	v_add_u32_e32 v142, s90, v212
	ds_read_b128 v[130:133], v142
	ds_read_b128 v[134:137], v142 offset:1024
	ds_read_b128 v[138:141], v142 offset:2048
	ds_read_b128 v[142:145], v142 offset:3072
	s_waitcnt vmcnt(6)
	s_barrier
	v_mfma_f32_16x16x32_bf16 v[54:57], v[178:181], v[146:149], 0
	v_mfma_f32_16x16x32_bf16 v[50:53], v[200:203], v[146:149], 0
	v_mfma_f32_16x16x32_bf16 v[38:41], v[178:181], v[154:157], 0
	v_mfma_f32_16x16x32_bf16 v[34:37], v[200:203], v[154:157], 0
	v_mfma_f32_16x16x32_bf16 v[22:25], v[178:181], v[162:165], 0
	v_mfma_f32_16x16x32_bf16 v[18:21], v[200:203], v[162:165], 0
	v_mfma_f32_16x16x32_bf16 v[6:9], v[178:181], v[170:173], 0
	v_mfma_f32_16x16x32_bf16 v[2:5], v[200:203], v[170:173], 0
	v_mfma_f32_16x16x32_bf16 v[54:57], v[182:185], v[150:153], v[54:57]
	v_mfma_f32_16x16x32_bf16 v[50:53], v[204:207], v[150:153], v[50:53]
	v_mfma_f32_16x16x32_bf16 v[38:41], v[182:185], v[158:161], v[38:41]
	v_mfma_f32_16x16x32_bf16 v[34:37], v[204:207], v[158:161], v[34:37]
	v_mfma_f32_16x16x32_bf16 v[22:25], v[182:185], v[166:169], v[22:25]
	v_mfma_f32_16x16x32_bf16 v[18:21], v[204:207], v[166:169], v[18:21]
	v_mfma_f32_16x16x32_bf16 v[6:9], v[182:185], v[174:177], v[6:9]
	v_mfma_f32_16x16x32_bf16 v[2:5], v[204:207], v[174:177], v[2:5]
	s_barrier
	s_add_u32 s16, s88, 0xb0000
	s_addc_u32 s17, s89, 0
	s_mov_b32 m0, s43
	ds_read_b128 v[146:149], v213 offset:32768
	ds_read_b128 v[150:153], v213 offset:33792
	ds_read_b128 v[154:157], v213 offset:34816
	ds_read_b128 v[158:161], v213 offset:35840
	ds_read_b128 v[162:165], v213 offset:36864
	ds_read_b128 v[166:169], v213 offset:37888
	ds_read_b128 v[170:173], v213 offset:38912
	global_load_lds_dwordx4 v190, s[16:17]
	s_mov_b32 m0, s44
	ds_read_b128 v[174:177], v213 offset:39936
	global_load_lds_dwordx4 v192, s[16:17]
	s_waitcnt lgkmcnt(8)
	s_barrier
	s_waitcnt lgkmcnt(0)
	v_mfma_f32_16x16x32_bf16 v[126:129], v[130:133], v[146:149], v[126:129]
	v_mfma_f32_16x16x32_bf16 v[122:125], v[138:141], v[146:149], v[122:125]
	v_mfma_f32_16x16x32_bf16 v[110:113], v[130:133], v[154:157], v[110:113]
	v_mfma_f32_16x16x32_bf16 v[106:109], v[138:141], v[154:157], v[106:109]
	v_mfma_f32_16x16x32_bf16 v[94:97], v[130:133], v[162:165], v[94:97]
	v_mfma_f32_16x16x32_bf16 v[90:93], v[138:141], v[162:165], v[90:93]
	v_mfma_f32_16x16x32_bf16 v[78:81], v[130:133], v[170:173], v[78:81]
	v_mfma_f32_16x16x32_bf16 v[74:77], v[138:141], v[170:173], v[74:77]
	v_mfma_f32_16x16x32_bf16 v[126:129], v[134:137], v[150:153], v[126:129]
	v_mfma_f32_16x16x32_bf16 v[122:125], v[142:145], v[150:153], v[122:125]
	v_mfma_f32_16x16x32_bf16 v[110:113], v[134:137], v[158:161], v[110:113]
	v_mfma_f32_16x16x32_bf16 v[106:109], v[142:145], v[158:161], v[106:109]
	v_mfma_f32_16x16x32_bf16 v[94:97], v[134:137], v[166:169], v[94:97]
	v_mfma_f32_16x16x32_bf16 v[90:93], v[142:145], v[166:169], v[90:93]
	v_mfma_f32_16x16x32_bf16 v[78:81], v[134:137], v[174:177], v[78:81]
	v_mfma_f32_16x16x32_bf16 v[74:77], v[142:145], v[174:177], v[74:77]
	s_barrier
	s_add_i32 s88, 0, 0x1c000
	v_add_u32_e32 v204, s88, v212
	s_add_i32 m0, s38, 0x18000
	ds_read_b128 v[178:181], v204
	ds_read_b128 v[182:185], v204 offset:1024
	ds_read_b128 v[200:203], v204 offset:2048
	ds_read_b128 v[204:207], v204 offset:3072
	s_add_u32 s98, s86, s40
	s_addc_u32 s99, s87, s41
	global_load_lds_dwordx4 v0, s[98:99]
	s_add_i32 m0, s38, 0x1a000
	s_nop 0
	global_load_lds_dwordx4 v194, s[98:99]
	s_barrier
	s_waitcnt lgkmcnt(0)
	v_mfma_f32_16x16x32_bf16 v[118:121], v[178:181], v[146:149], v[118:121]
	v_mfma_f32_16x16x32_bf16 v[114:117], v[200:203], v[146:149], v[114:117]
	v_mfma_f32_16x16x32_bf16 v[102:105], v[178:181], v[154:157], v[102:105]
	v_mfma_f32_16x16x32_bf16 v[98:101], v[200:203], v[154:157], v[98:101]
	v_mfma_f32_16x16x32_bf16 v[86:89], v[178:181], v[162:165], v[86:89]
	v_mfma_f32_16x16x32_bf16 v[82:85], v[200:203], v[162:165], v[82:85]
	v_mfma_f32_16x16x32_bf16 v[70:73], v[178:181], v[170:173], v[70:73]
	v_mfma_f32_16x16x32_bf16 v[66:69], v[200:203], v[170:173], v[66:69]
	v_mfma_f32_16x16x32_bf16 v[118:121], v[182:185], v[150:153], v[118:121]
	v_mfma_f32_16x16x32_bf16 v[114:117], v[204:207], v[150:153], v[114:117]
	v_mfma_f32_16x16x32_bf16 v[102:105], v[182:185], v[158:161], v[102:105]
	v_mfma_f32_16x16x32_bf16 v[98:101], v[204:207], v[158:161], v[98:101]
	v_mfma_f32_16x16x32_bf16 v[86:89], v[182:185], v[166:169], v[86:89]
	v_mfma_f32_16x16x32_bf16 v[82:85], v[204:207], v[166:169], v[82:85]
	v_mfma_f32_16x16x32_bf16 v[70:73], v[182:185], v[174:177], v[70:73]
	v_mfma_f32_16x16x32_bf16 v[66:69], v[204:207], v[174:177], v[66:69]
	s_mov_b32 m0, s60
	s_barrier
	ds_read_b128 v[146:149], v213 offset:49152
	ds_read_b128 v[150:153], v213 offset:50176
	ds_read_b128 v[154:157], v213 offset:51200
	ds_read_b128 v[158:161], v213 offset:52224
	ds_read_b128 v[162:165], v213 offset:53248
	ds_read_b128 v[166:169], v213 offset:54272
	ds_read_b128 v[170:173], v213 offset:55296
	ds_read_b128 v[174:177], v213 offset:56320
	s_add_u32 s98, s100, s40
	s_addc_u32 s99, s101, s41
	global_load_lds_dwordx4 v190, s[98:99]
	s_mov_b32 m0, s61
	s_nop 0
	global_load_lds_dwordx4 v192, s[98:99]
	s_waitcnt vmcnt(10)
	s_barrier
	s_waitcnt lgkmcnt(0)
	v_mfma_f32_16x16x32_bf16 v[62:65], v[130:133], v[146:149], v[62:65]
	v_mfma_f32_16x16x32_bf16 v[58:61], v[138:141], v[146:149], v[58:61]
	v_mfma_f32_16x16x32_bf16 v[46:49], v[130:133], v[154:157], v[46:49]
	v_mfma_f32_16x16x32_bf16 v[42:45], v[138:141], v[154:157], v[42:45]
	v_mfma_f32_16x16x32_bf16 v[30:33], v[130:133], v[162:165], v[30:33]
	v_mfma_f32_16x16x32_bf16 v[26:29], v[138:141], v[162:165], v[26:29]
	v_mfma_f32_16x16x32_bf16 v[14:17], v[130:133], v[170:173], v[14:17]
	v_mfma_f32_16x16x32_bf16 v[10:13], v[138:141], v[170:173], v[10:13]
	v_mfma_f32_16x16x32_bf16 v[62:65], v[134:137], v[150:153], v[62:65]
	v_mfma_f32_16x16x32_bf16 v[58:61], v[142:145], v[150:153], v[58:61]
	v_mfma_f32_16x16x32_bf16 v[46:49], v[134:137], v[158:161], v[46:49]
	v_mfma_f32_16x16x32_bf16 v[42:45], v[142:145], v[158:161], v[42:45]
	v_mfma_f32_16x16x32_bf16 v[30:33], v[134:137], v[166:169], v[30:33]
	v_mfma_f32_16x16x32_bf16 v[26:29], v[142:145], v[166:169], v[26:29]
	v_mfma_f32_16x16x32_bf16 v[14:17], v[134:137], v[174:177], v[14:17]
	v_mfma_f32_16x16x32_bf16 v[10:13], v[142:145], v[174:177], v[10:13]
	s_barrier
	s_add_u32 s16, s86, 0xb0080
	s_addc_u32 s17, s87, 0
	s_add_i32 m0, s38, 0x1c000
	s_nop 0
	global_load_lds_dwordx4 v0, s[16:17]
	s_add_i32 m0, s38, 0x1e000
	s_nop 0
	global_load_lds_dwordx4 v194, s[16:17]
	ds_read_b128 v[130:133], v189
	ds_read_b128 v[134:137], v189 offset:1024
	ds_read_b128 v[138:141], v189 offset:2048
	ds_read_b128 v[142:145], v189 offset:3072
	s_waitcnt vmcnt(6)
	s_barrier
	v_mfma_f32_16x16x32_bf16 v[54:57], v[178:181], v[146:149], v[54:57]
	v_mfma_f32_16x16x32_bf16 v[50:53], v[200:203], v[146:149], v[50:53]
	v_mfma_f32_16x16x32_bf16 v[38:41], v[178:181], v[154:157], v[38:41]
	v_mfma_f32_16x16x32_bf16 v[34:37], v[200:203], v[154:157], v[34:37]
	v_mfma_f32_16x16x32_bf16 v[22:25], v[178:181], v[162:165], v[22:25]
	v_mfma_f32_16x16x32_bf16 v[18:21], v[200:203], v[162:165], v[18:21]
	v_mfma_f32_16x16x32_bf16 v[6:9], v[178:181], v[170:173], v[6:9]
	v_mfma_f32_16x16x32_bf16 v[2:5], v[200:203], v[170:173], v[2:5]
	v_mfma_f32_16x16x32_bf16 v[54:57], v[182:185], v[150:153], v[54:57]
	v_mfma_f32_16x16x32_bf16 v[50:53], v[204:207], v[150:153], v[50:53]
	v_mfma_f32_16x16x32_bf16 v[38:41], v[182:185], v[158:161], v[38:41]
	v_mfma_f32_16x16x32_bf16 v[34:37], v[204:207], v[158:161], v[34:37]
	v_mfma_f32_16x16x32_bf16 v[22:25], v[182:185], v[166:169], v[22:25]
	v_mfma_f32_16x16x32_bf16 v[18:21], v[204:207], v[166:169], v[18:21]
	v_mfma_f32_16x16x32_bf16 v[6:9], v[182:185], v[174:177], v[6:9]
	v_mfma_f32_16x16x32_bf16 v[2:5], v[204:207], v[174:177], v[2:5]
	s_add_i32 s79, s79, 2
	s_add_u32 s34, s34, 0x100
	s_addc_u32 s78, s78, 0
	s_mov_b64 s[16:17], s[84:85]
	s_add_u32 s84, s16, 0x100
	s_addc_u32 s85, s17, 0
	s_cmp_eq_u32 s79, 40
	s_cselect_b32 s89, s5, s85
	s_cselect_b32 s88, s4, s84
	s_cselect_b32 s87, s7, s78
	s_cselect_b32 s86, s6, s34
	s_cmp_gt_u32 s79, 41
	s_barrier
	.p2align 3

.LBB0_1208:
	s_ashr_i32 s13, s12, 31
	v_cmp_lt_i64_e32 vcc, s[14:15], v[230:231]
	s_lshl_b64 s[14:15], s[12:13], 19
	s_add_u32 s14, s80, s14
	s_addc_u32 s15, s81, s15
	s_and_b64 s[16:17], vcc, exec
	s_cselect_b32 s13, s15, s89
	s_cselect_b32 s22, s14, s88
	s_ashr_i32 s7, s6, 31
	s_lshl_b64 s[16:17], s[6:7], 19
	s_add_u32 s16, s36, s16
	s_addc_u32 s17, s37, s17
	s_and_b64 s[92:93], vcc, exec
	s_cselect_b32 s7, s17, s91
	s_cselect_b32 s23, s16, s90
	s_add_u32 s88, s88, 0x40080
	s_addc_u32 s89, s89, 0
	s_add_u32 s34, s90, 0x100
	s_addc_u32 s79, s91, 0
	s_mov_b32 s85, -2
	s_waitcnt lgkmcnt(0)
	s_add_i32 s94, 0, 0x10000
	v_add_u32_e32 v0, s94, v170
	v_add_u32_e32 v189, 0x10000, v170
	ds_read_b128 v[130:133], v0
	ds_read_b128 v[134:137], v0 offset:1024
	ds_read_b128 v[138:141], v0 offset:2048
	ds_read_b128 v[142:145], v0 offset:3072
	s_add_u32 s87, s88, 0xfffc0080
	s_addc_u32 s90, s89, -1
	s_cmp_eq_u32 s85, 12
	s_cselect_b32 s93, s13, s90
	s_cselect_b32 s92, s22, s87
	s_cselect_b32 s91, s7, s79
	s_cselect_b32 s90, s23, s34
	s_waitcnt lgkmcnt(0)
	s_add_i32 m0, s39, 0xc000
	ds_read_b128 v[158:161], v171
	ds_read_b128 v[162:165], v171 offset:1024
	ds_read_b128 v[166:169], v171 offset:2048
	ds_read_b128 v[172:175], v171 offset:3072
	ds_read_b128 v[176:179], v171 offset:4096
	ds_read_b128 v[180:183], v171 offset:5120
	ds_read_b128 v[184:187], v171 offset:6144
	global_load_lds_dwordx4 v154, s[88:89]
	s_add_i32 m0, s39, 0xe000
	ds_read_b128 v[190:193], v171 offset:7168
	global_load_lds_dwordx4 v156, s[88:89]
	s_waitcnt lgkmcnt(8)
	s_barrier
	s_waitcnt lgkmcnt(0)
	v_mfma_f32_16x16x32_bf16 v[126:129], v[130:133], v[158:161], 0
	v_mfma_f32_16x16x32_bf16 v[122:125], v[138:141], v[158:161], 0
	v_mfma_f32_16x16x32_bf16 v[110:113], v[130:133], v[166:169], 0
	v_mfma_f32_16x16x32_bf16 v[106:109], v[138:141], v[166:169], 0
	v_mfma_f32_16x16x32_bf16 v[94:97], v[130:133], v[176:179], 0
	v_mfma_f32_16x16x32_bf16 v[90:93], v[138:141], v[176:179], 0
	v_mfma_f32_16x16x32_bf16 v[78:81], v[130:133], v[184:187], 0
	v_mfma_f32_16x16x32_bf16 v[74:77], v[138:141], v[184:187], 0
	v_mfma_f32_16x16x32_bf16 v[126:129], v[134:137], v[162:165], v[126:129]
	v_mfma_f32_16x16x32_bf16 v[122:125], v[142:145], v[162:165], v[122:125]
	v_mfma_f32_16x16x32_bf16 v[110:113], v[134:137], v[172:175], v[110:113]
	v_mfma_f32_16x16x32_bf16 v[106:109], v[142:145], v[172:175], v[106:109]
	v_mfma_f32_16x16x32_bf16 v[94:97], v[134:137], v[180:183], v[94:97]
	v_mfma_f32_16x16x32_bf16 v[90:93], v[142:145], v[180:183], v[90:93]
	v_mfma_f32_16x16x32_bf16 v[78:81], v[134:137], v[190:193], v[78:81]
	v_mfma_f32_16x16x32_bf16 v[74:77], v[142:145], v[190:193], v[74:77]
	s_barrier
	s_add_i32 m0, s38, 0x10000
	ds_read_b128 v[194:197], v189 offset:16384
	ds_read_b128 v[198:201], v189 offset:17408
	ds_read_b128 v[202:205], v189 offset:18432
	global_load_lds_dwordx4 v148, s[90:91]
	s_add_i32 m0, s38, 0x12000
	ds_read_b128 v[206:209], v189 offset:19456
	global_load_lds_dwordx4 v152, s[90:91]
	s_barrier
	s_waitcnt lgkmcnt(0)
	v_mfma_f32_16x16x32_bf16 v[118:121], v[194:197], v[158:161], 0
	v_mfma_f32_16x16x32_bf16 v[114:117], v[202:205], v[158:161], 0
	v_mfma_f32_16x16x32_bf16 v[102:105], v[194:197], v[166:169], 0
	v_mfma_f32_16x16x32_bf16 v[98:101], v[202:205], v[166:169], 0
	v_mfma_f32_16x16x32_bf16 v[86:89], v[194:197], v[176:179], 0
	v_mfma_f32_16x16x32_bf16 v[82:85], v[202:205], v[176:179], 0
	v_mfma_f32_16x16x32_bf16 v[70:73], v[194:197], v[184:187], 0
	v_mfma_f32_16x16x32_bf16 v[66:69], v[202:205], v[184:187], 0
	v_mfma_f32_16x16x32_bf16 v[118:121], v[198:201], v[162:165], v[118:121]
	v_mfma_f32_16x16x32_bf16 v[114:117], v[206:209], v[162:165], v[114:117]
	v_mfma_f32_16x16x32_bf16 v[102:105], v[198:201], v[172:175], v[102:105]
	v_mfma_f32_16x16x32_bf16 v[98:101], v[206:209], v[172:175], v[98:101]
	v_mfma_f32_16x16x32_bf16 v[86:89], v[198:201], v[180:183], v[86:89]
	v_mfma_f32_16x16x32_bf16 v[82:85], v[206:209], v[180:183], v[82:85]
	v_mfma_f32_16x16x32_bf16 v[70:73], v[198:201], v[190:193], v[70:73]
	v_mfma_f32_16x16x32_bf16 v[66:69], v[206:209], v[190:193], v[66:69]
	s_mov_b32 m0, s39
	s_mov_b64 s[100:101], s[92:93]
	s_barrier
	ds_read_b128 v[158:161], v171 offset:16384
	ds_read_b128 v[162:165], v171 offset:17408
	ds_read_b128 v[166:169], v171 offset:18432
	ds_read_b128 v[172:175], v171 offset:19456
	ds_read_b128 v[176:179], v171 offset:20480
	ds_read_b128 v[180:183], v171 offset:21504
	ds_read_b128 v[184:187], v171 offset:22528
	global_load_lds_dwordx4 v146, s[100:101]
	s_mov_b32 m0, s42
	ds_read_b128 v[190:193], v171 offset:23552
	global_load_lds_dwordx4 v150, s[100:101]
	s_waitcnt vmcnt(10)
	s_barrier
	s_waitcnt lgkmcnt(0)
	v_mfma_f32_16x16x32_bf16 v[62:65], v[130:133], v[158:161], 0
	v_mfma_f32_16x16x32_bf16 v[58:61], v[138:141], v[158:161], 0
	v_mfma_f32_16x16x32_bf16 v[46:49], v[130:133], v[166:169], 0
	v_mfma_f32_16x16x32_bf16 v[42:45], v[138:141], v[166:169], 0
	v_mfma_f32_16x16x32_bf16 v[30:33], v[130:133], v[176:179], 0
	v_mfma_f32_16x16x32_bf16 v[26:29], v[138:141], v[176:179], 0
	v_mfma_f32_16x16x32_bf16 v[14:17], v[130:133], v[184:187], 0
	v_mfma_f32_16x16x32_bf16 v[10:13], v[138:141], v[184:187], 0
	v_mfma_f32_16x16x32_bf16 v[62:65], v[134:137], v[162:165], v[62:65]
	v_mfma_f32_16x16x32_bf16 v[58:61], v[142:145], v[162:165], v[58:61]
	v_mfma_f32_16x16x32_bf16 v[46:49], v[134:137], v[172:175], v[46:49]
	v_mfma_f32_16x16x32_bf16 v[42:45], v[142:145], v[172:175], v[42:45]
	v_mfma_f32_16x16x32_bf16 v[30:33], v[134:137], v[180:183], v[30:33]
	v_mfma_f32_16x16x32_bf16 v[26:29], v[142:145], v[180:183], v[26:29]
	v_mfma_f32_16x16x32_bf16 v[14:17], v[134:137], v[190:193], v[14:17]
	v_mfma_f32_16x16x32_bf16 v[10:13], v[142:145], v[190:193], v[10:13]
	s_barrier
	s_add_u32 s94, s90, 0x40000
	s_addc_u32 s95, s91, 0
	s_add_i32 m0, s38, 0x14000
	s_nop 0
	global_load_lds_dwordx4 v148, s[94:95]
	s_add_i32 m0, s38, 0x16000
	s_nop 0
	global_load_lds_dwordx4 v152, s[94:95]
	ds_read_b128 v[130:133], v189 offset:32768
	ds_read_b128 v[134:137], v189 offset:33792
	ds_read_b128 v[138:141], v189 offset:34816
	ds_read_b128 v[142:145], v189 offset:35840
	s_waitcnt vmcnt(6)
	s_barrier
	v_mfma_f32_16x16x32_bf16 v[54:57], v[194:197], v[158:161], 0
	v_mfma_f32_16x16x32_bf16 v[50:53], v[202:205], v[158:161], 0
	v_mfma_f32_16x16x32_bf16 v[38:41], v[194:197], v[166:169], 0
	v_mfma_f32_16x16x32_bf16 v[34:37], v[202:205], v[166:169], 0
	v_mfma_f32_16x16x32_bf16 v[22:25], v[194:197], v[176:179], 0
	v_mfma_f32_16x16x32_bf16 v[18:21], v[202:205], v[176:179], 0
	v_mfma_f32_16x16x32_bf16 v[6:9], v[194:197], v[184:187], 0
	v_mfma_f32_16x16x32_bf16 v[2:5], v[202:205], v[184:187], 0
	v_mfma_f32_16x16x32_bf16 v[54:57], v[198:201], v[162:165], v[54:57]
	v_mfma_f32_16x16x32_bf16 v[50:53], v[206:209], v[162:165], v[50:53]
	v_mfma_f32_16x16x32_bf16 v[38:41], v[198:201], v[172:175], v[38:41]
	v_mfma_f32_16x16x32_bf16 v[34:37], v[206:209], v[172:175], v[34:37]
	v_mfma_f32_16x16x32_bf16 v[22:25], v[198:201], v[180:183], v[22:25]
	v_mfma_f32_16x16x32_bf16 v[18:21], v[206:209], v[180:183], v[18:21]
	v_mfma_f32_16x16x32_bf16 v[6:9], v[198:201], v[190:193], v[6:9]
	v_mfma_f32_16x16x32_bf16 v[2:5], v[206:209], v[190:193], v[2:5]
	s_barrier
	s_add_u32 s92, s92, 0x40000
	s_addc_u32 s93, s93, 0
	s_mov_b32 m0, s43
	ds_read_b128 v[158:161], v171 offset:32768
	ds_read_b128 v[162:165], v171 offset:33792
	ds_read_b128 v[166:169], v171 offset:34816
	ds_read_b128 v[172:175], v171 offset:35840
	ds_read_b128 v[176:179], v171 offset:36864
	ds_read_b128 v[180:183], v171 offset:37888
	ds_read_b128 v[184:187], v171 offset:38912
	global_load_lds_dwordx4 v146, s[92:93]
	s_mov_b32 m0, s44
	ds_read_b128 v[190:193], v171 offset:39936
	global_load_lds_dwordx4 v150, s[92:93]
	s_waitcnt lgkmcnt(8)
	s_barrier
	s_waitcnt lgkmcnt(0)
	v_mfma_f32_16x16x32_bf16 v[126:129], v[130:133], v[158:161], v[126:129]
	v_mfma_f32_16x16x32_bf16 v[122:125], v[138:141], v[158:161], v[122:125]
	v_mfma_f32_16x16x32_bf16 v[110:113], v[130:133], v[166:169], v[110:113]
	v_mfma_f32_16x16x32_bf16 v[106:109], v[138:141], v[166:169], v[106:109]
	v_mfma_f32_16x16x32_bf16 v[94:97], v[130:133], v[176:179], v[94:97]
	v_mfma_f32_16x16x32_bf16 v[90:93], v[138:141], v[176:179], v[90:93]
	v_mfma_f32_16x16x32_bf16 v[78:81], v[130:133], v[184:187], v[78:81]
	v_mfma_f32_16x16x32_bf16 v[74:77], v[138:141], v[184:187], v[74:77]
	v_mfma_f32_16x16x32_bf16 v[126:129], v[134:137], v[162:165], v[126:129]
	v_mfma_f32_16x16x32_bf16 v[122:125], v[142:145], v[162:165], v[122:125]
	v_mfma_f32_16x16x32_bf16 v[110:113], v[134:137], v[172:175], v[110:113]
	v_mfma_f32_16x16x32_bf16 v[106:109], v[142:145], v[172:175], v[106:109]
	v_mfma_f32_16x16x32_bf16 v[94:97], v[134:137], v[180:183], v[94:97]
	v_mfma_f32_16x16x32_bf16 v[90:93], v[142:145], v[180:183], v[90:93]
	v_mfma_f32_16x16x32_bf16 v[78:81], v[134:137], v[190:193], v[78:81]
	v_mfma_f32_16x16x32_bf16 v[74:77], v[142:145], v[190:193], v[74:77]
	s_barrier
	s_add_i32 m0, s38, 0x18000
	ds_read_b128 v[194:197], v189 offset:49152
	ds_read_b128 v[198:201], v189 offset:50176
	ds_read_b128 v[202:205], v189 offset:51200
	ds_read_b128 v[206:209], v189 offset:52224
	s_add_u32 s98, s90, s40
	s_addc_u32 s99, s91, s41
	global_load_lds_dwordx4 v148, s[98:99]
	s_add_i32 m0, s38, 0x1a000
	s_nop 0
	global_load_lds_dwordx4 v152, s[98:99]
	s_barrier
	s_waitcnt lgkmcnt(0)
	v_mfma_f32_16x16x32_bf16 v[118:121], v[194:197], v[158:161], v[118:121]
	v_mfma_f32_16x16x32_bf16 v[114:117], v[202:205], v[158:161], v[114:117]
	v_mfma_f32_16x16x32_bf16 v[102:105], v[194:197], v[166:169], v[102:105]
	v_mfma_f32_16x16x32_bf16 v[98:101], v[202:205], v[166:169], v[98:101]
	v_mfma_f32_16x16x32_bf16 v[86:89], v[194:197], v[176:179], v[86:89]
	v_mfma_f32_16x16x32_bf16 v[82:85], v[202:205], v[176:179], v[82:85]
	v_mfma_f32_16x16x32_bf16 v[70:73], v[194:197], v[184:187], v[70:73]
	v_mfma_f32_16x16x32_bf16 v[66:69], v[202:205], v[184:187], v[66:69]
	v_mfma_f32_16x16x32_bf16 v[118:121], v[198:201], v[162:165], v[118:121]
	v_mfma_f32_16x16x32_bf16 v[114:117], v[206:209], v[162:165], v[114:117]
	v_mfma_f32_16x16x32_bf16 v[102:105], v[198:201], v[172:175], v[102:105]
	v_mfma_f32_16x16x32_bf16 v[98:101], v[206:209], v[172:175], v[98:101]
	v_mfma_f32_16x16x32_bf16 v[86:89], v[198:201], v[180:183], v[86:89]
	v_mfma_f32_16x16x32_bf16 v[82:85], v[206:209], v[180:183], v[82:85]
	v_mfma_f32_16x16x32_bf16 v[70:73], v[198:201], v[190:193], v[70:73]
	v_mfma_f32_16x16x32_bf16 v[66:69], v[206:209], v[190:193], v[66:69]
	s_mov_b32 m0, s60
	s_barrier
	ds_read_b128 v[158:161], v171 offset:49152
	ds_read_b128 v[162:165], v171 offset:50176
	ds_read_b128 v[166:169], v171 offset:51200
	ds_read_b128 v[172:175], v171 offset:52224
	ds_read_b128 v[176:179], v171 offset:53248
	ds_read_b128 v[180:183], v171 offset:54272
	ds_read_b128 v[184:187], v171 offset:55296
	ds_read_b128 v[190:193], v171 offset:56320
	s_add_u32 s98, s100, s40
	s_addc_u32 s99, s101, s41
	global_load_lds_dwordx4 v146, s[98:99]
	s_mov_b32 m0, s61
	s_nop 0
	global_load_lds_dwordx4 v150, s[98:99]
	s_waitcnt vmcnt(10)
	s_barrier
	s_waitcnt lgkmcnt(0)
	v_mfma_f32_16x16x32_bf16 v[62:65], v[130:133], v[158:161], v[62:65]
	v_mfma_f32_16x16x32_bf16 v[58:61], v[138:141], v[158:161], v[58:61]
	v_mfma_f32_16x16x32_bf16 v[46:49], v[130:133], v[166:169], v[46:49]
	v_mfma_f32_16x16x32_bf16 v[42:45], v[138:141], v[166:169], v[42:45]
	v_mfma_f32_16x16x32_bf16 v[30:33], v[130:133], v[176:179], v[30:33]
	v_mfma_f32_16x16x32_bf16 v[26:29], v[138:141], v[176:179], v[26:29]
	v_mfma_f32_16x16x32_bf16 v[14:17], v[130:133], v[184:187], v[14:17]
	v_mfma_f32_16x16x32_bf16 v[10:13], v[138:141], v[184:187], v[10:13]
	v_mfma_f32_16x16x32_bf16 v[62:65], v[134:137], v[162:165], v[62:65]
	v_mfma_f32_16x16x32_bf16 v[58:61], v[142:145], v[162:165], v[58:61]
	v_mfma_f32_16x16x32_bf16 v[46:49], v[134:137], v[172:175], v[46:49]
	v_mfma_f32_16x16x32_bf16 v[42:45], v[142:145], v[172:175], v[42:45]
	v_mfma_f32_16x16x32_bf16 v[30:33], v[134:137], v[180:183], v[30:33]
	v_mfma_f32_16x16x32_bf16 v[26:29], v[142:145], v[180:183], v[26:29]
	v_mfma_f32_16x16x32_bf16 v[14:17], v[134:137], v[190:193], v[14:17]
	v_mfma_f32_16x16x32_bf16 v[10:13], v[142:145], v[190:193], v[10:13]
	s_barrier
	s_add_u32 s90, s90, 0x40080
	s_addc_u32 s91, s91, 0
	s_add_i32 m0, s38, 0x1c000
	s_nop 0
	global_load_lds_dwordx4 v148, s[90:91]
	s_add_i32 m0, s38, 0x1e000
	s_nop 0
	global_load_lds_dwordx4 v152, s[90:91]
	ds_read_b128 v[130:133], v189
	ds_read_b128 v[134:137], v189 offset:1024
	ds_read_b128 v[138:141], v189 offset:2048
	ds_read_b128 v[142:145], v189 offset:3072
	s_waitcnt vmcnt(6)
	s_barrier
	v_mfma_f32_16x16x32_bf16 v[54:57], v[194:197], v[158:161], v[54:57]
	v_mfma_f32_16x16x32_bf16 v[50:53], v[202:205], v[158:161], v[50:53]
	v_mfma_f32_16x16x32_bf16 v[38:41], v[194:197], v[166:169], v[38:41]
	v_mfma_f32_16x16x32_bf16 v[34:37], v[202:205], v[166:169], v[34:37]
	v_mfma_f32_16x16x32_bf16 v[22:25], v[194:197], v[176:179], v[22:25]
	v_mfma_f32_16x16x32_bf16 v[18:21], v[202:205], v[176:179], v[18:21]
	v_mfma_f32_16x16x32_bf16 v[6:9], v[194:197], v[184:187], v[6:9]
	v_mfma_f32_16x16x32_bf16 v[2:5], v[202:205], v[184:187], v[2:5]
	v_mfma_f32_16x16x32_bf16 v[54:57], v[198:201], v[162:165], v[54:57]
	v_mfma_f32_16x16x32_bf16 v[50:53], v[206:209], v[162:165], v[50:53]
	v_mfma_f32_16x16x32_bf16 v[38:41], v[198:201], v[172:175], v[38:41]
	v_mfma_f32_16x16x32_bf16 v[34:37], v[206:209], v[172:175], v[34:37]
	v_mfma_f32_16x16x32_bf16 v[22:25], v[198:201], v[180:183], v[22:25]
	v_mfma_f32_16x16x32_bf16 v[18:21], v[206:209], v[180:183], v[18:21]
	v_mfma_f32_16x16x32_bf16 v[6:9], v[198:201], v[190:193], v[6:9]
	v_mfma_f32_16x16x32_bf16 v[2:5], v[206:209], v[190:193], v[2:5]
	s_add_i32 s85, s85, 2
	s_add_u32 s88, s88, 0x100
	s_addc_u32 s89, s89, 0
	s_add_u32 s34, s34, 0x100
	s_addc_u32 s79, s79, 0
	s_add_u32 s87, s88, 0xfffc0080
	s_addc_u32 s90, s89, -1
	s_cmp_eq_u32 s85, 12
	s_cselect_b32 s93, s13, s90
	s_cselect_b32 s92, s22, s87
	s_cselect_b32 s91, s7, s79
	s_cselect_b32 s90, s23, s34
	s_cmp_gt_u32 s85, 13
	s_barrier
	.p2align 3
